# P5 tail round split-K across CU pairs (write-through partial exchange, uneven 26/18 K split); retention state-init loads batched; first K-iteration peeled (no accumulator zeroing)
# speedup vs baseline: 1.0842x; 1.0266x over previous
; #define PG8_STAGE(bufoff, gbase, voff) do { _Pragma("unroll") for (int _i = 0; _i < 2; ++_i) \
;         __builtin_amdgcn_global_load_lds((const unsigned*)((const char*)(gbase) + (voff)[_i]), (PG8_LAS unsigned*)(lds + (bufoff) + ldsw + _i * 8192), 16, 0, 0); } while (0)
; #define PG8_LDA(dst, b, h) do { _Pragma("unroll") for (int m = 0; m < 4; ++m) _Pragma("unroll") for (int k = 0; k < 2; ++k) dst[m][k] = *(const PG8_LAS bf16x8*)(lds + PG8_SA(b, h) + aoff + m * 2048 + k * 1024); } while (0)
; #define PG8_LDB(dst, b, h) do { _Pragma("unroll") for (int n = 0; n < 2; ++n) _Pragma("unroll") for (int k = 0; k < 2; ++k) dst[n][k] = *(const PG8_LAS bf16x8*)(lds + PG8_SB(b, h) + boff + n * 2048 + k * 1024); } while (0)
; #define PG8_WAIT_V(n) asm volatile("s_waitcnt vmcnt(" #n ")" ::: "memory")
; #define PG8_WAIT_L(n) asm volatile("s_waitcnt lgkmcnt(" #n ")" ::: "memory")
; #define PG8_BAR __builtin_amdgcn_s_barrier()
; #define PG8_SCHED __builtin_amdgcn_sched_barrier(0)
; template <class Epi, class Sched, bool ALIGN_EPI = false, bool SP2 = false>
; __device__ __forceinline__ void gemm_phase(PG8_LAS unsigned char* lds, const Gemm g, const Sched& S, const Epi& E) {
;     ...
;         for (int t = 0; t < nt; t += 2) {
;             const bool last = (t == nt - 2);
;             const char* a1 = cA + (size_t)(t + 1) * kstep;
;             const char* a2 = last ? nA : cA + (size_t)(t + 2) * kstep; const char* b2 = last ? nB : cB + (size_t)(t + 2) * kstep;
;             const char* a3 = a2 + kstep; const char* b3 = b2 + kstep;
;             if (last && has_next) S.a_ready(nxt);
;             if constexpr (SP2) {
;             PG8_LDB(B0, 0, 0); PG8_LDB(B1, 0, 1); PG8_SCHED; PG8_LDA(At, 0, 0); PG8_STAGE(PG8_SA(1, 1), a1 + hstep, voffA);
;             PG8_WAIT_V(8); PG8_WAIT_L(0); PG8_BAR; PG8_MMA(0, 0, At, B0); PG8_MMA(0, 1, At, B1); PG8_BAR; PG8_SCHED;
;             PG8_LDA(At, 0, 1); PG8_STAGE(PG8_SB(0, 0), b2, voffB); PG8_STAGE(PG8_SB(0, 1), b2 + hstep, voffB); PG8_STAGE(PG8_SA(0, 0), a2, voffA);
;             PG8_WAIT_V(8); PG8_WAIT_L(0); PG8_BAR; PG8_MMA(1, 0, At, B0); PG8_MMA(1, 1, At, B1); PG8_BAR; PG8_SCHED;
;             PG8_LDB(B0, 1, 0); PG8_LDB(B1, 1, 1); PG8_SCHED; PG8_LDA(At, 1, 0); PG8_STAGE(PG8_SA(0, 1), a2 + hstep, voffA);
;             PG8_WAIT_V(8); PG8_WAIT_L(0); PG8_BAR; PG8_MMA(0, 0, At, B0); PG8_MMA(0, 1, At, B1); PG8_BAR; PG8_SCHED;
.LBB0_131:
	s_ashr_i32 s1, s0, 31
	s_lshl_b64 s[14:15], s[0:1], 19
	s_add_u32 s94, s50, s14
	s_addc_u32 s95, s51, s15
	s_and_b64 s[14:15], s[6:7], exec
	s_cselect_b32 s1, s95, s9
	s_cselect_b32 s16, s94, s8
	s_ashr_i32 s89, s88, 31
	s_lshl_b64 s[14:15], s[88:89], 19
	s_add_u32 s96, s33, s14
	s_addc_u32 s97, s42, s15
	s_and_b64 s[14:15], s[6:7], exec
	s_cselect_b32 s30, s97, s11
	s_cselect_b32 s31, s96, s10
	s_add_u32 s8, s8, 0x40080
	s_addc_u32 s9, s9, 0
	s_add_u32 s34, s10, 0x100
	s_addc_u32 s35, s11, 0
	s_mov_b32 s36, -2
	s_waitcnt lgkmcnt(0)
	ds_read_b128 v[128:131], v194
	ds_read_b128 v[132:135], v194 offset:1024
	ds_read_b128 v[136:139], v194 offset:2048
	ds_read_b128 v[140:143], v194 offset:3072
	ds_read_b128 v[166:169], v195
	ds_read_b128 v[202:205], v195 offset:1024
	ds_read_b128 v[206:209], v195 offset:2048
	ds_read_b128 v[210:213], v195 offset:3072
	s_add_u32 s10, s8, 0xfffc0080
	s_addc_u32 s11, s9, -1
	s_cmp_eq_u32 s36, 12
	s_cselect_b32 s15, s1, s11
	s_cselect_b32 s14, s16, s10
	s_cselect_b32 s11, s30, s35
	s_cselect_b32 s10, s31, s34
	v_lshl_add_u64 v[170:171], s[8:9], 0, v[156:157]
	s_add_i32 m0, s91, 0xc000
	ds_read_b128 v[214:217], v196
	ds_read_b128 v[218:221], v196 offset:1024
	ds_read_b128 v[222:225], v196 offset:2048
	ds_read_b128 v[226:229], v196 offset:3072
	ds_read_b128 v[230:233], v196 offset:4096
	ds_read_b128 v[234:237], v196 offset:5120
	ds_read_b128 v[238:241], v196 offset:6144
	ds_read_b128 v[242:245], v196 offset:7168
	global_load_lds_dwordx4 v[170:171], off
	v_lshl_add_u64 v[170:171], s[8:9], 0, v[158:159]
	s_add_i32 m0, s91, 0xe000
	s_nop 0
	global_load_lds_dwordx4 v[170:171], off
	s_waitcnt vmcnt(8)
	s_waitcnt lgkmcnt(0)
	s_barrier
	s_setprio 1
	s_waitcnt lgkmcnt(0)
	v_mfma_f32_16x16x32_bf16 v[124:127], v[128:131], v[214:217], 0
	v_mfma_f32_16x16x32_bf16 v[120:123], v[136:139], v[214:217], 0
	v_mfma_f32_16x16x32_bf16 v[108:111], v[128:131], v[222:225], 0
	v_mfma_f32_16x16x32_bf16 v[104:107], v[136:139], v[222:225], 0
	v_mfma_f32_16x16x32_bf16 v[92:95], v[128:131], v[230:233], 0
	v_mfma_f32_16x16x32_bf16 v[88:91], v[136:139], v[230:233], 0
	v_mfma_f32_16x16x32_bf16 v[76:79], v[128:131], v[238:241], 0
	v_mfma_f32_16x16x32_bf16 v[72:75], v[136:139], v[238:241], 0
	v_mfma_f32_16x16x32_bf16 v[124:127], v[132:135], v[218:221], v[124:127]
	v_mfma_f32_16x16x32_bf16 v[120:123], v[140:143], v[218:221], v[120:123]
	v_mfma_f32_16x16x32_bf16 v[108:111], v[132:135], v[226:229], v[108:111]
	v_mfma_f32_16x16x32_bf16 v[104:107], v[140:143], v[226:229], v[104:107]
	v_mfma_f32_16x16x32_bf16 v[92:95], v[132:135], v[234:237], v[92:95]
	v_mfma_f32_16x16x32_bf16 v[88:91], v[140:143], v[234:237], v[88:91]
	v_mfma_f32_16x16x32_bf16 v[76:79], v[132:135], v[242:245], v[76:79]
	v_mfma_f32_16x16x32_bf16 v[72:75], v[140:143], v[242:245], v[72:75]
	s_setprio 0
	s_setprio 1
	v_mfma_f32_16x16x32_bf16 v[116:119], v[166:169], v[214:217], 0
	v_mfma_f32_16x16x32_bf16 v[112:115], v[206:209], v[214:217], 0
	v_mfma_f32_16x16x32_bf16 v[100:103], v[166:169], v[222:225], 0
	v_mfma_f32_16x16x32_bf16 v[96:99], v[206:209], v[222:225], 0
	v_mfma_f32_16x16x32_bf16 v[84:87], v[166:169], v[230:233], 0
	v_mfma_f32_16x16x32_bf16 v[80:83], v[206:209], v[230:233], 0
	v_mfma_f32_16x16x32_bf16 v[68:71], v[166:169], v[238:241], 0
	v_mfma_f32_16x16x32_bf16 v[64:67], v[206:209], v[238:241], 0
	v_mfma_f32_16x16x32_bf16 v[116:119], v[202:205], v[218:221], v[116:119]
	v_mfma_f32_16x16x32_bf16 v[112:115], v[210:213], v[218:221], v[112:115]
	v_mfma_f32_16x16x32_bf16 v[100:103], v[202:205], v[226:229], v[100:103]
	v_mfma_f32_16x16x32_bf16 v[96:99], v[210:213], v[226:229], v[96:99]
	v_mfma_f32_16x16x32_bf16 v[84:87], v[202:205], v[234:237], v[84:87]
	v_mfma_f32_16x16x32_bf16 v[80:83], v[210:213], v[234:237], v[80:83]
	v_mfma_f32_16x16x32_bf16 v[68:71], v[202:205], v[242:245], v[68:71]
	v_mfma_f32_16x16x32_bf16 v[64:67], v[210:213], v[242:245], v[64:67]
	s_setprio 0
	s_barrier
	s_add_i32 s37, s82, s43
	v_lshl_add_u64 v[170:171], s[10:11], 0, v[146:147]
	s_mov_b32 m0, s37
	ds_read_b128 v[214:217], v196 offset:16384
	ds_read_b128 v[218:221], v196 offset:17408
	ds_read_b128 v[222:225], v196 offset:18432
	ds_read_b128 v[226:229], v196 offset:19456
	ds_read_b128 v[230:233], v196 offset:20480
	ds_read_b128 v[234:237], v196 offset:21504
	ds_read_b128 v[238:241], v196 offset:22528
	ds_read_b128 v[242:245], v196 offset:23552
	global_load_lds_dwordx4 v[170:171], off
	s_add_i32 m0, s37, 0x2000
	s_add_u32 s38, s10, 0x40000
	v_lshl_add_u64 v[246:247], s[10:11], 0, v[150:151]
	s_addc_u32 s39, s11, 0
	s_add_i32 s37, s83, s43
	global_load_lds_dwordx4 v[246:247], off
	v_lshl_add_u64 v[248:249], s[38:39], 0, v[146:147]
	s_mov_b32 m0, s37
	v_lshl_add_u64 v[250:251], s[14:15], 0, v[148:149]
	global_load_lds_dwordx4 v[248:249], off
	v_lshl_add_u64 v[248:249], s[38:39], 0, v[150:151]
	s_add_i32 m0, s37, 0x2000
	s_nop 0
	global_load_lds_dwordx4 v[248:249], off
	v_lshl_add_u64 v[248:249], s[14:15], 0, v[144:145]
	s_mov_b32 m0, s91
	s_nop 0
	global_load_lds_dwordx4 v[248:249], off
	s_mov_b32 m0, s93
	s_nop 0
	global_load_lds_dwordx4 v[250:251], off
	s_waitcnt vmcnt(8)
	s_waitcnt lgkmcnt(0)
	s_barrier
; #define PG8_STAGE(bufoff, gbase, voff) do { _Pragma("unroll") for (int _i = 0; _i < 2; ++_i) \
;         __builtin_amdgcn_global_load_lds((const unsigned*)((const char*)(gbase) + (voff)[_i]), (PG8_LAS unsigned*)(lds + (bufoff) + ldsw + _i * 8192), 16, 0, 0); } while (0)
; #define PG8_LDA(dst, b, h) do { _Pragma("unroll") for (int m = 0; m < 4; ++m) _Pragma("unroll") for (int k = 0; k < 2; ++k) dst[m][k] = *(const PG8_LAS bf16x8*)(lds + PG8_SA(b, h) + aoff + m * 2048 + k * 1024); } while (0)
; #define PG8_LDB(dst, b, h) do { _Pragma("unroll") for (int n = 0; n < 2; ++n) _Pragma("unroll") for (int k = 0; k < 2; ++k) dst[n][k] = *(const PG8_LAS bf16x8*)(lds + PG8_SB(b, h) + boff + n * 2048 + k * 1024); } while (0)
; #define PG8_MMA(ai, bj, At, Bt) do { __builtin_amdgcn_s_setprio(1); _Pragma("unroll") for (int m = 0; m < 4; ++m) _Pragma("unroll") for (int n = 0; n < 2; ++n) _Pragma("unroll") for (int k = 0; k < 2; ++k) \
;         acc[ai][bj][m][n] = __builtin_amdgcn_mfma_f32_16x16x32_bf16(Bt[n][k], At[m][k], acc[ai][bj][m][n], 0, 0, 0); __builtin_amdgcn_s_setprio(0); } while (0)
; #define PG8_WAIT_V(n) asm volatile("s_waitcnt vmcnt(" #n ")" ::: "memory")
; #define PG8_WAIT_L(n) asm volatile("s_waitcnt lgkmcnt(" #n ")" ::: "memory")
; #define PG8_BAR __builtin_amdgcn_s_barrier()
; #define PG8_SCHED __builtin_amdgcn_sched_barrier(0)
; template <class Epi, class Sched, bool ALIGN_EPI = false, bool SP2 = false>
; __device__ __forceinline__ void gemm_phase(PG8_LAS unsigned char* lds, const Gemm g, const Sched& S, const Epi& E) {
;     ...
;             PG8_LDB(B0, 0, 0); PG8_LDB(B1, 0, 1); PG8_SCHED; PG8_LDA(At, 0, 0); PG8_STAGE(PG8_SA(1, 1), a1 + hstep, voffA);
;             PG8_WAIT_V(8); PG8_WAIT_L(0); PG8_BAR; PG8_MMA(0, 0, At, B0); PG8_MMA(0, 1, At, B1); PG8_BAR; PG8_SCHED;
;             PG8_LDA(At, 0, 1); PG8_STAGE(PG8_SB(0, 0), b2, voffB); PG8_STAGE(PG8_SB(0, 1), b2 + hstep, voffB); PG8_STAGE(PG8_SA(0, 0), a2, voffA);
;             PG8_WAIT_V(8); PG8_WAIT_L(0); PG8_BAR; PG8_MMA(1, 0, At, B0); PG8_MMA(1, 1, At, B1); PG8_BAR; PG8_SCHED;
;             PG8_LDB(B0, 1, 0); PG8_LDB(B1, 1, 1); PG8_SCHED; PG8_LDA(At, 1, 0); PG8_STAGE(PG8_SA(0, 1), a2 + hstep, voffA);
;             PG8_WAIT_V(8); PG8_WAIT_L(0); PG8_BAR; PG8_MMA(0, 0, At, B0); PG8_MMA(0, 1, At, B1); PG8_BAR; PG8_SCHED;
	s_setprio 1
	s_waitcnt lgkmcnt(0)
	v_mfma_f32_16x16x32_bf16 v[60:63], v[128:131], v[214:217], 0
	v_mfma_f32_16x16x32_bf16 v[56:59], v[136:139], v[214:217], 0
	v_mfma_f32_16x16x32_bf16 v[44:47], v[128:131], v[222:225], 0
	v_mfma_f32_16x16x32_bf16 v[40:43], v[136:139], v[222:225], 0
	v_mfma_f32_16x16x32_bf16 v[28:31], v[128:131], v[230:233], 0
	v_mfma_f32_16x16x32_bf16 v[24:27], v[136:139], v[230:233], 0
	v_mfma_f32_16x16x32_bf16 v[12:15], v[128:131], v[238:241], 0
	v_mfma_f32_16x16x32_bf16 v[8:11], v[136:139], v[238:241], 0
	v_mfma_f32_16x16x32_bf16 v[60:63], v[132:135], v[218:221], v[60:63]
	v_mfma_f32_16x16x32_bf16 v[56:59], v[140:143], v[218:221], v[56:59]
	v_mfma_f32_16x16x32_bf16 v[44:47], v[132:135], v[226:229], v[44:47]
	v_mfma_f32_16x16x32_bf16 v[40:43], v[140:143], v[226:229], v[40:43]
	v_mfma_f32_16x16x32_bf16 v[28:31], v[132:135], v[234:237], v[28:31]
	v_mfma_f32_16x16x32_bf16 v[24:27], v[140:143], v[234:237], v[24:27]
	v_mfma_f32_16x16x32_bf16 v[12:15], v[132:135], v[242:245], v[12:15]
	v_mfma_f32_16x16x32_bf16 v[8:11], v[140:143], v[242:245], v[8:11]
	s_setprio 0
	s_setprio 1
	v_mfma_f32_16x16x32_bf16 v[52:55], v[166:169], v[214:217], 0
	v_mfma_f32_16x16x32_bf16 v[48:51], v[206:209], v[214:217], 0
	v_mfma_f32_16x16x32_bf16 v[36:39], v[166:169], v[222:225], 0
	v_mfma_f32_16x16x32_bf16 v[32:35], v[206:209], v[222:225], 0
	v_mfma_f32_16x16x32_bf16 v[20:23], v[166:169], v[230:233], 0
	v_mfma_f32_16x16x32_bf16 v[16:19], v[206:209], v[230:233], 0
	v_mfma_f32_16x16x32_bf16 v[4:7], v[166:169], v[238:241], 0
	v_mfma_f32_16x16x32_bf16 v[0:3], v[206:209], v[238:241], 0
	v_mfma_f32_16x16x32_bf16 v[52:55], v[202:205], v[218:221], v[52:55]
	v_mfma_f32_16x16x32_bf16 v[48:51], v[210:213], v[218:221], v[48:51]
	v_mfma_f32_16x16x32_bf16 v[36:39], v[202:205], v[226:229], v[36:39]
	v_mfma_f32_16x16x32_bf16 v[32:35], v[210:213], v[226:229], v[32:35]
	v_mfma_f32_16x16x32_bf16 v[20:23], v[202:205], v[234:237], v[20:23]
	v_mfma_f32_16x16x32_bf16 v[16:19], v[210:213], v[234:237], v[16:19]
	v_mfma_f32_16x16x32_bf16 v[4:7], v[202:205], v[242:245], v[4:7]
	v_mfma_f32_16x16x32_bf16 v[0:3], v[210:213], v[242:245], v[0:3]
	s_setprio 0
	s_barrier
	s_add_i32 s37, 0, 0x18000
	s_add_i32 s38, 0, 0x1c000
	v_add_u32_e32 v140, s37, v173
	v_add_u32_e32 v152, s38, v173
	ds_read_b128 v[128:131], v140
	ds_read_b128 v[132:135], v140 offset:1024
	ds_read_b128 v[136:139], v140 offset:2048
	ds_read_b128 v[140:143], v140 offset:3072
	ds_read_b128 v[166:169], v152
	ds_read_b128 v[202:205], v152 offset:1024
	ds_read_b128 v[206:209], v152 offset:2048
	ds_read_b128 v[210:213], v152 offset:3072
	s_add_u32 s14, s14, 0x40000
	s_addc_u32 s15, s15, 0
	s_mov_b32 m0, s52
	v_lshl_add_u64 v[252:253], s[14:15], 0, v[144:145]
	ds_read_b128 v[214:217], v196 offset:32768
	ds_read_b128 v[218:221], v196 offset:33792
	ds_read_b128 v[222:225], v196 offset:34816
	ds_read_b128 v[226:229], v196 offset:35840
	ds_read_b128 v[230:233], v196 offset:36864
	ds_read_b128 v[234:237], v196 offset:37888
	ds_read_b128 v[238:241], v196 offset:38912
	ds_read_b128 v[242:245], v196 offset:39936
	global_load_lds_dwordx4 v[252:253], off
	v_lshl_add_u64 v[252:253], s[14:15], 0, v[148:149]
	s_mov_b32 m0, s53
	s_nop 0
	global_load_lds_dwordx4 v[252:253], off
	s_waitcnt vmcnt(8)
	s_waitcnt lgkmcnt(0)
	s_barrier
	s_setprio 1
	s_waitcnt lgkmcnt(0)
	v_mfma_f32_16x16x32_bf16 v[124:127], v[128:131], v[214:217], v[124:127]
	v_mfma_f32_16x16x32_bf16 v[120:123], v[136:139], v[214:217], v[120:123]
	v_mfma_f32_16x16x32_bf16 v[108:111], v[128:131], v[222:225], v[108:111]
	v_mfma_f32_16x16x32_bf16 v[104:107], v[136:139], v[222:225], v[104:107]
	v_mfma_f32_16x16x32_bf16 v[92:95], v[128:131], v[230:233], v[92:95]
	v_mfma_f32_16x16x32_bf16 v[88:91], v[136:139], v[230:233], v[88:91]
	v_mfma_f32_16x16x32_bf16 v[76:79], v[128:131], v[238:241], v[76:79]
	v_mfma_f32_16x16x32_bf16 v[72:75], v[136:139], v[238:241], v[72:75]
	v_mfma_f32_16x16x32_bf16 v[124:127], v[132:135], v[218:221], v[124:127]
	v_mfma_f32_16x16x32_bf16 v[120:123], v[140:143], v[218:221], v[120:123]
	v_mfma_f32_16x16x32_bf16 v[108:111], v[132:135], v[226:229], v[108:111]
	v_mfma_f32_16x16x32_bf16 v[104:107], v[140:143], v[226:229], v[104:107]
	v_mfma_f32_16x16x32_bf16 v[92:95], v[132:135], v[234:237], v[92:95]
	v_mfma_f32_16x16x32_bf16 v[88:91], v[140:143], v[234:237], v[88:91]
	v_mfma_f32_16x16x32_bf16 v[76:79], v[132:135], v[242:245], v[76:79]
	v_mfma_f32_16x16x32_bf16 v[72:75], v[140:143], v[242:245], v[72:75]
	s_setprio 0
	s_setprio 1
	v_mfma_f32_16x16x32_bf16 v[116:119], v[166:169], v[214:217], v[116:119]
	v_mfma_f32_16x16x32_bf16 v[112:115], v[206:209], v[214:217], v[112:115]
	v_mfma_f32_16x16x32_bf16 v[100:103], v[166:169], v[222:225], v[100:103]
	v_mfma_f32_16x16x32_bf16 v[96:99], v[206:209], v[222:225], v[96:99]
	v_mfma_f32_16x16x32_bf16 v[84:87], v[166:169], v[230:233], v[84:87]
	v_mfma_f32_16x16x32_bf16 v[80:83], v[206:209], v[230:233], v[80:83]
	v_mfma_f32_16x16x32_bf16 v[68:71], v[166:169], v[238:241], v[68:71]
	v_mfma_f32_16x16x32_bf16 v[64:67], v[206:209], v[238:241], v[64:67]
	v_mfma_f32_16x16x32_bf16 v[116:119], v[202:205], v[218:221], v[116:119]
	v_mfma_f32_16x16x32_bf16 v[112:115], v[210:213], v[218:221], v[112:115]
	v_mfma_f32_16x16x32_bf16 v[100:103], v[202:205], v[226:229], v[100:103]
	v_mfma_f32_16x16x32_bf16 v[96:99], v[210:213], v[226:229], v[96:99]
	v_mfma_f32_16x16x32_bf16 v[84:87], v[202:205], v[234:237], v[84:87]
	v_mfma_f32_16x16x32_bf16 v[80:83], v[210:213], v[234:237], v[80:83]
	v_mfma_f32_16x16x32_bf16 v[68:71], v[202:205], v[242:245], v[68:71]
	v_mfma_f32_16x16x32_bf16 v[64:67], v[210:213], v[242:245], v[64:67]
	s_setprio 0
	s_barrier
; #define PG8_STAGE(bufoff, gbase, voff) do { _Pragma("unroll") for (int _i = 0; _i < 2; ++_i) \
;         __builtin_amdgcn_global_load_lds((const unsigned*)((const char*)(gbase) + (voff)[_i]), (PG8_LAS unsigned*)(lds + (bufoff) + ldsw + _i * 8192), 16, 0, 0); } while (0)
; #define PG8_LDA(dst, b, h) do { _Pragma("unroll") for (int m = 0; m < 4; ++m) _Pragma("unroll") for (int k = 0; k < 2; ++k) dst[m][k] = *(const PG8_LAS bf16x8*)(lds + PG8_SA(b, h) + aoff + m * 2048 + k * 1024); } while (0)
; #define PG8_LDB(dst, b, h) do { _Pragma("unroll") for (int n = 0; n < 2; ++n) _Pragma("unroll") for (int k = 0; k < 2; ++k) dst[n][k] = *(const PG8_LAS bf16x8*)(lds + PG8_SB(b, h) + boff + n * 2048 + k * 1024); } while (0)
; #define PG8_MMA(ai, bj, At, Bt) do { __builtin_amdgcn_s_setprio(1); _Pragma("unroll") for (int m = 0; m < 4; ++m) _Pragma("unroll") for (int n = 0; n < 2; ++n) _Pragma("unroll") for (int k = 0; k < 2; ++k) \
;         acc[ai][bj][m][n] = __builtin_amdgcn_mfma_f32_16x16x32_bf16(Bt[n][k], At[m][k], acc[ai][bj][m][n], 0, 0, 0); __builtin_amdgcn_s_setprio(0); } while (0)
; #define PG8_WAIT_V(n) asm volatile("s_waitcnt vmcnt(" #n ")" ::: "memory")
; #define PG8_WAIT_L(n) asm volatile("s_waitcnt lgkmcnt(" #n ")" ::: "memory")
; #define PG8_BAR __builtin_amdgcn_s_barrier()
; #define PG8_SCHED __builtin_amdgcn_sched_barrier(0)
; template <class Epi, class Sched, bool ALIGN_EPI = false, bool SP2 = false>
; __device__ __forceinline__ void gemm_phase(PG8_LAS unsigned char* lds, const Gemm g, const Sched& S, const Epi& E) {
;     ...
;         for (int t = 0; t < nt; t += 2) {
;     ...
;             PG8_LDB(B0, 1, 0); PG8_LDB(B1, 1, 1); PG8_SCHED; PG8_LDA(At, 1, 0); PG8_STAGE(PG8_SA(0, 1), a2 + hstep, voffA);
;             PG8_WAIT_V(8); PG8_WAIT_L(0); PG8_BAR; PG8_MMA(0, 0, At, B0); PG8_MMA(0, 1, At, B1); PG8_BAR; PG8_SCHED;
;             PG8_LDA(At, 1, 1); PG8_STAGE(PG8_SB(1, 0), b3, voffB); PG8_STAGE(PG8_SB(1, 1), b3 + hstep, voffB); PG8_STAGE(PG8_SA(1, 0), a3, voffA);
;             PG8_WAIT_V(8); PG8_WAIT_L(0); PG8_BAR; PG8_MMA(1, 0, At, B0); PG8_MMA(1, 1, At, B1); PG8_BAR; PG8_SCHED;
	s_add_i32 s14, s37, s43
	v_lshl_add_u64 v[170:171], v[170:171], 0, s[20:21]
	s_mov_b32 m0, s14
	ds_read_b128 v[214:217], v196 offset:49152
	ds_read_b128 v[218:221], v196 offset:50176
	ds_read_b128 v[222:225], v196 offset:51200
	ds_read_b128 v[226:229], v196 offset:52224
	ds_read_b128 v[230:233], v196 offset:53248
	ds_read_b128 v[234:237], v196 offset:54272
	ds_read_b128 v[238:241], v196 offset:55296
	ds_read_b128 v[242:245], v196 offset:56320
	global_load_lds_dwordx4 v[170:171], off
	s_add_i32 m0, s14, 0x2000
	s_add_u32 s10, s10, 0x40080
	v_lshl_add_u64 v[170:171], v[246:247], 0, s[20:21]
	s_addc_u32 s11, s11, 0
	s_add_i32 s14, s38, s43
	global_load_lds_dwordx4 v[170:171], off
	v_lshl_add_u64 v[170:171], s[10:11], 0, v[146:147]
	s_mov_b32 m0, s14
	s_nop 0
	global_load_lds_dwordx4 v[170:171], off
	v_lshl_add_u64 v[170:171], s[10:11], 0, v[150:151]
	s_add_i32 m0, s14, 0x2000
	s_nop 0
	global_load_lds_dwordx4 v[170:171], off
	v_lshl_add_u64 v[170:171], v[248:249], 0, s[20:21]
	s_mov_b32 m0, s55
	s_nop 0
	global_load_lds_dwordx4 v[170:171], off
	v_lshl_add_u64 v[170:171], v[250:251], 0, s[20:21]
	s_mov_b32 m0, s70
	s_nop 0
	global_load_lds_dwordx4 v[170:171], off
	s_waitcnt vmcnt(8)
	s_waitcnt lgkmcnt(0)
	s_barrier
	s_setprio 1
	s_waitcnt lgkmcnt(0)
	v_mfma_f32_16x16x32_bf16 v[60:63], v[128:131], v[214:217], v[60:63]
	v_mfma_f32_16x16x32_bf16 v[56:59], v[136:139], v[214:217], v[56:59]
	v_mfma_f32_16x16x32_bf16 v[44:47], v[128:131], v[222:225], v[44:47]
	v_mfma_f32_16x16x32_bf16 v[40:43], v[136:139], v[222:225], v[40:43]
	v_mfma_f32_16x16x32_bf16 v[28:31], v[128:131], v[230:233], v[28:31]
	v_mfma_f32_16x16x32_bf16 v[24:27], v[136:139], v[230:233], v[24:27]
	v_mfma_f32_16x16x32_bf16 v[12:15], v[128:131], v[238:241], v[12:15]
	v_mfma_f32_16x16x32_bf16 v[8:11], v[136:139], v[238:241], v[8:11]
	v_mfma_f32_16x16x32_bf16 v[60:63], v[132:135], v[218:221], v[60:63]
	v_mfma_f32_16x16x32_bf16 v[56:59], v[140:143], v[218:221], v[56:59]
	v_mfma_f32_16x16x32_bf16 v[44:47], v[132:135], v[226:229], v[44:47]
	v_mfma_f32_16x16x32_bf16 v[40:43], v[140:143], v[226:229], v[40:43]
	v_mfma_f32_16x16x32_bf16 v[28:31], v[132:135], v[234:237], v[28:31]
	v_mfma_f32_16x16x32_bf16 v[24:27], v[140:143], v[234:237], v[24:27]
	v_mfma_f32_16x16x32_bf16 v[12:15], v[132:135], v[242:245], v[12:15]
	v_mfma_f32_16x16x32_bf16 v[8:11], v[140:143], v[242:245], v[8:11]
	s_setprio 0
	s_setprio 1
	v_mfma_f32_16x16x32_bf16 v[52:55], v[166:169], v[214:217], v[52:55]
	v_mfma_f32_16x16x32_bf16 v[48:51], v[206:209], v[214:217], v[48:51]
	v_mfma_f32_16x16x32_bf16 v[36:39], v[166:169], v[222:225], v[36:39]
	v_mfma_f32_16x16x32_bf16 v[32:35], v[206:209], v[222:225], v[32:35]
	v_mfma_f32_16x16x32_bf16 v[20:23], v[166:169], v[230:233], v[20:23]
	v_mfma_f32_16x16x32_bf16 v[16:19], v[206:209], v[230:233], v[16:19]
	v_mfma_f32_16x16x32_bf16 v[4:7], v[166:169], v[238:241], v[4:7]
	v_mfma_f32_16x16x32_bf16 v[0:3], v[206:209], v[238:241], v[0:3]
	v_mfma_f32_16x16x32_bf16 v[52:55], v[202:205], v[218:221], v[52:55]
	v_mfma_f32_16x16x32_bf16 v[48:51], v[210:213], v[218:221], v[48:51]
	v_mfma_f32_16x16x32_bf16 v[36:39], v[202:205], v[226:229], v[36:39]
	v_mfma_f32_16x16x32_bf16 v[32:35], v[210:213], v[226:229], v[32:35]
	v_mfma_f32_16x16x32_bf16 v[20:23], v[202:205], v[234:237], v[20:23]
	v_mfma_f32_16x16x32_bf16 v[16:19], v[210:213], v[234:237], v[16:19]
	v_mfma_f32_16x16x32_bf16 v[4:7], v[202:205], v[242:245], v[4:7]
	v_mfma_f32_16x16x32_bf16 v[0:3], v[210:213], v[242:245], v[0:3]
	s_setprio 0
	s_barrier
	s_add_i32 s36, s36, 2
	s_add_u32 s8, s8, 0x100
	s_addc_u32 s9, s9, 0
	s_add_u32 s34, s34, 0x100
	s_addc_u32 s35, s35, 0
	s_cmp_gt_u32 s36, 13

; DI int crow(int r, int hi) { return (r & 3) + 8 * (r >> 2) + 4 * hi; }
; DI void ret_unit(const Params& p, LAS unsigned char* ldsu, int mode, int b, int hp, int seg) {
;     ...
;     else if (mode == 1 && seg > 0) {
;         if (tid == 0) { for (int sp = 0; sp < seg; ++sp) while (__hip_atomic_load(flags + sp, __ATOMIC_RELAXED, __HIP_MEMORY_SCOPE_AGENT) == 0u) __builtin_amdgcn_s_sleep(2);
;             __builtin_amdgcn_fence(__ATOMIC_ACQUIRE, "agent"); asm volatile("s_waitcnt vmcnt(0)" ::: "memory"); }
;         __syncthreads();
;         for (int sp = 0; sp < seg; ++sp) { const float w = exp2f(512.f * (float)(seg - 1 - sp) * lg2); const float* tp = Tb + (size_t)sp * 8192;
; #pragma unroll
;             for (int ks = 0; ks < 2; ++ks)
; #pragma unroll
;                 for (int i = 0; i < 16; ++i) S[ks][i] += w * __builtin_nontemporal_load(tp + (size_t)(32 * ks + crow(i, hh)) * 128); }
.LBB0_634:
	v_cvt_f32_i32_e32 v0, s9
	v_mul_f32_e32 v0, 0x44000000, v0
	v_mul_f32_e32 v36, v197, v0
	v_cmp_gt_f32_e32 vcc, s85, v36
	s_and_b64 s[6:7], vcc, exec
	s_cselect_b32 s6, 0xffffffc0, 0
	v_cndmask_b32_e32 v36, 0, v191, vcc
	v_fmac_f32_e32 v36, v197, v0
	v_exp_f32_e32 v0, v36
	v_add_co_u32_e32 v36, vcc, s15, v2
	s_nop 1
	v_addc_co_u32_e32 v37, vcc, 0, v3, vcc
	v_add_co_u32_e32 v38, vcc, s15, v36
	s_nop 1
	v_addc_co_u32_e32 v39, vcc, 0, v37, vcc
	v_add_co_u32_e32 v44, vcc, s15, v38
	s_nop 1
	v_addc_co_u32_e32 v45, vcc, 0, v39, vcc
	v_add_co_u32_e32 v46, vcc, s15, v44
	s_nop 1
	v_addc_co_u32_e32 v47, vcc, 0, v45, vcc
	global_load_dword v222, v[2:3], off nt
	global_load_dword v223, v[2:3], off offset:512 nt
	global_load_dword v224, v[2:3], off offset:1024 nt
	global_load_dword v225, v[2:3], off offset:1536 nt
	global_load_dword v226, v[36:37], off offset:-4096 nt
	global_load_dword v227, v[36:37], off offset:-3584 nt
	global_load_dword v228, v[36:37], off offset:-3072 nt
	global_load_dword v229, v[36:37], off offset:-2560 nt
	global_load_dword v230, v[36:37], off nt
	global_load_dword v231, v[36:37], off offset:512 nt
	global_load_dword v232, v[36:37], off offset:1024 nt
	global_load_dword v233, v[36:37], off offset:1536 nt
	global_load_dword v234, v[38:39], off offset:-4096 nt
	global_load_dword v235, v[38:39], off offset:-3584 nt
	global_load_dword v236, v[38:39], off offset:-3072 nt
	global_load_dword v237, v[38:39], off offset:-2560 nt
	global_load_dword v238, v[38:39], off nt
	global_load_dword v239, v[38:39], off offset:512 nt
	global_load_dword v240, v[38:39], off offset:1024 nt
	global_load_dword v241, v[38:39], off offset:1536 nt
	global_load_dword v242, v[44:45], off offset:-4096 nt
	global_load_dword v243, v[44:45], off offset:-3584 nt
	global_load_dword v244, v[44:45], off offset:-3072 nt
	global_load_dword v245, v[44:45], off offset:-2560 nt
	global_load_dword v246, v[44:45], off nt
	global_load_dword v247, v[44:45], off offset:512 nt
	global_load_dword v248, v[44:45], off offset:1024 nt
	global_load_dword v249, v[44:45], off offset:1536 nt
	global_load_dword v250, v[46:47], off offset:-4096 nt
	global_load_dword v251, v[46:47], off offset:-3584 nt
	global_load_dword v252, v[46:47], off offset:-3072 nt
	global_load_dword v253, v[46:47], off offset:-2560 nt
	s_add_i32 s8, s8, -1
	s_add_i32 s9, s9, -1
	v_ldexp_f32 v0, v0, s6
	s_mov_b64 s[6:7], 0x8000
	s_cmp_lg_u32 s8, 0
	s_waitcnt vmcnt(24)
	v_pk_fma_f32 v[20:21], v[0:1], v[222:223], v[20:21] op_sel_hi:[0,1,1]
	v_pk_fma_f32 v[22:23], v[0:1], v[224:225], v[22:23] op_sel_hi:[0,1,1]
	v_pk_fma_f32 v[24:25], v[0:1], v[226:227], v[24:25] op_sel_hi:[0,1,1]
	v_pk_fma_f32 v[26:27], v[0:1], v[228:229], v[26:27] op_sel_hi:[0,1,1]
	s_waitcnt vmcnt(16)
	v_pk_fma_f32 v[28:29], v[0:1], v[230:231], v[28:29] op_sel_hi:[0,1,1]
	v_pk_fma_f32 v[30:31], v[0:1], v[232:233], v[30:31] op_sel_hi:[0,1,1]
	v_pk_fma_f32 v[32:33], v[0:1], v[234:235], v[32:33] op_sel_hi:[0,1,1]
	v_pk_fma_f32 v[34:35], v[0:1], v[236:237], v[34:35] op_sel_hi:[0,1,1]
	s_waitcnt vmcnt(8)
	v_pk_fma_f32 v[4:5], v[0:1], v[238:239], v[4:5] op_sel_hi:[0,1,1]
	v_pk_fma_f32 v[6:7], v[0:1], v[240:241], v[6:7] op_sel_hi:[0,1,1]
	v_pk_fma_f32 v[8:9], v[0:1], v[242:243], v[8:9] op_sel_hi:[0,1,1]
	v_pk_fma_f32 v[10:11], v[0:1], v[244:245], v[10:11] op_sel_hi:[0,1,1]
	s_waitcnt vmcnt(0)
	v_pk_fma_f32 v[12:13], v[0:1], v[246:247], v[12:13] op_sel_hi:[0,1,1]
	v_pk_fma_f32 v[14:15], v[0:1], v[248:249], v[14:15] op_sel_hi:[0,1,1]
	v_pk_fma_f32 v[16:17], v[0:1], v[250:251], v[16:17] op_sel_hi:[0,1,1]
	v_pk_fma_f32 v[18:19], v[0:1], v[252:253], v[18:19] op_sel_hi:[0,1,1]
	v_lshl_add_u64 v[2:3], v[2:3], 0, s[6:7]
	s_cbranch_scc1 .LBB0_634
	s_mov_b32 s14, 64
	s_mov_b32 s95, 8

; #define PG8_STAGE(bufoff, gbase, voff) do { _Pragma("unroll") for (int _i = 0; _i < 2; ++_i) \
;         __builtin_amdgcn_global_load_lds((const unsigned*)((const char*)(gbase) + (voff)[_i]), (PG8_LAS unsigned*)(lds + (bufoff) + ldsw + _i * 8192), 16, 0, 0); } while (0)
; #define PG8_LDA(dst, b, h) do { _Pragma("unroll") for (int m = 0; m < 4; ++m) _Pragma("unroll") for (int k = 0; k < 2; ++k) dst[m][k] = *(const PG8_LAS bf16x8*)(lds + PG8_SA(b, h) + aoff + m * 2048 + k * 1024); } while (0)
; #define PG8_LDB(dst, b, h) do { _Pragma("unroll") for (int n = 0; n < 2; ++n) _Pragma("unroll") for (int k = 0; k < 2; ++k) dst[n][k] = *(const PG8_LAS bf16x8*)(lds + PG8_SB(b, h) + boff + n * 2048 + k * 1024); } while (0)
; #define PG8_WAIT_V(n) asm volatile("s_waitcnt vmcnt(" #n ")" ::: "memory")
; #define PG8_WAIT_L(n) asm volatile("s_waitcnt lgkmcnt(" #n ")" ::: "memory")
; #define PG8_BAR __builtin_amdgcn_s_barrier()
; #define PG8_SCHED __builtin_amdgcn_sched_barrier(0)
; template <class Epi, class Sched, bool ALIGN_EPI = false, bool SP2 = false>
; __device__ __forceinline__ void gemm_phase(PG8_LAS unsigned char* lds, const Gemm g, const Sched& S, const Epi& E) {
;     ...
;         for (int t = 0; t < nt; t += 2) {
;             const bool last = (t == nt - 2);
;             const char* a1 = cA + (size_t)(t + 1) * kstep;
;             const char* a2 = last ? nA : cA + (size_t)(t + 2) * kstep; const char* b2 = last ? nB : cB + (size_t)(t + 2) * kstep;
;             const char* a3 = a2 + kstep; const char* b3 = b2 + kstep;
;             if (last && has_next) S.a_ready(nxt);
;             if constexpr (SP2) {
;             PG8_LDB(B0, 0, 0); PG8_LDB(B1, 0, 1); PG8_SCHED; PG8_LDA(At, 0, 0); PG8_STAGE(PG8_SA(1, 1), a1 + hstep, voffA);
;             PG8_WAIT_V(8); PG8_WAIT_L(0); PG8_BAR; PG8_MMA(0, 0, At, B0); PG8_MMA(0, 1, At, B1); PG8_BAR; PG8_SCHED;
;             PG8_LDA(At, 0, 1); PG8_STAGE(PG8_SB(0, 0), b2, voffB); PG8_STAGE(PG8_SB(0, 1), b2 + hstep, voffB); PG8_STAGE(PG8_SA(0, 0), a2, voffA);
;             PG8_WAIT_V(8); PG8_WAIT_L(0); PG8_BAR; PG8_MMA(1, 0, At, B0); PG8_MMA(1, 1, At, B1); PG8_BAR; PG8_SCHED;
;             PG8_LDB(B0, 1, 0); PG8_LDB(B1, 1, 1); PG8_SCHED; PG8_LDA(At, 1, 0); PG8_STAGE(PG8_SA(0, 1), a2 + hstep, voffA);
;             PG8_WAIT_V(8); PG8_WAIT_L(0); PG8_BAR; PG8_MMA(0, 0, At, B0); PG8_MMA(0, 1, At, B1); PG8_BAR; PG8_SCHED;
.LBB0_809:
	s_ashr_i32 s23, s22, 31
	s_lshl_b64 s[24:25], s[22:23], 19
	s_add_u32 s24, s33, s24
	s_addc_u32 s25, s84, s25
	s_and_b64 s[26:27], s[8:9], exec
	s_cselect_b32 s23, s25, s31
	s_cselect_b32 s29, s24, s30
	s_ashr_i32 s21, s20, 31
	s_lshl_b64 s[26:27], s[20:21], 19
	s_add_u32 s26, s34, s26
	s_addc_u32 s27, s35, s27
	s_and_b64 s[38:39], s[8:9], exec
	s_cselect_b32 s21, s27, s37
	s_cselect_b32 s58, s26, s36
	s_add_u32 s30, s30, 0x40080
	s_addc_u32 s31, s31, 0
	s_add_u32 s59, s36, 0x100
	s_addc_u32 s60, s37, 0
	s_mov_b32 s61, -2
	s_waitcnt lgkmcnt(0)
	s_waitcnt vmcnt(0)
	ds_read_b128 v[144:147], v151
	ds_read_b128 v[154:157], v151 offset:1024
	ds_read_b128 v[158:161], v151 offset:2048
	ds_read_b128 v[162:165], v151 offset:3072
	ds_read_b128 v[166:169], v152
	ds_read_b128 v[170:173], v152 offset:1024
	ds_read_b128 v[174:177], v152 offset:2048
	ds_read_b128 v[178:181], v152 offset:3072
	s_add_u32 s36, s30, 0xfffc0080
	s_addc_u32 s37, s31, -1
	s_cmp_eq_u32 s61, 12
	s_cselect_b32 s39, s23, s37
	s_cselect_b32 s38, s29, s36
	s_cselect_b32 s37, s21, s60
	s_cselect_b32 s36, s58, s59
	v_lshl_add_u64 v[220:221], s[30:31], 0, v[136:137]
	s_add_i32 m0, s41, 0xc000
	ds_read_b128 v[188:191], v153
	ds_read_b128 v[192:195], v153 offset:1024
	ds_read_b128 v[196:199], v153 offset:2048
	ds_read_b128 v[200:203], v153 offset:3072
	ds_read_b128 v[204:207], v153 offset:4096
	ds_read_b128 v[208:211], v153 offset:5120
	ds_read_b128 v[212:215], v153 offset:6144
	ds_read_b128 v[216:219], v153 offset:7168
	global_load_lds_dwordx4 v[220:221], off
	v_lshl_add_u64 v[220:221], s[30:31], 0, v[138:139]
	s_add_i32 m0, s41, 0xe000
	s_nop 0
	global_load_lds_dwordx4 v[220:221], off
	s_waitcnt vmcnt(8)
	s_waitcnt lgkmcnt(0)
	s_barrier
	s_setprio 1
	s_waitcnt lgkmcnt(0)
	v_mfma_f32_16x16x32_bf16 v[124:127], v[144:147], v[188:191], 0
	v_mfma_f32_16x16x32_bf16 v[120:123], v[158:161], v[188:191], 0
	v_mfma_f32_16x16x32_bf16 v[108:111], v[144:147], v[196:199], 0
	v_mfma_f32_16x16x32_bf16 v[104:107], v[158:161], v[196:199], 0
	v_mfma_f32_16x16x32_bf16 v[92:95], v[144:147], v[204:207], 0
	v_mfma_f32_16x16x32_bf16 v[88:91], v[158:161], v[204:207], 0
	v_mfma_f32_16x16x32_bf16 v[76:79], v[144:147], v[212:215], 0
	v_mfma_f32_16x16x32_bf16 v[72:75], v[158:161], v[212:215], 0
	v_mfma_f32_16x16x32_bf16 v[124:127], v[154:157], v[192:195], v[124:127]
	v_mfma_f32_16x16x32_bf16 v[120:123], v[162:165], v[192:195], v[120:123]
	v_mfma_f32_16x16x32_bf16 v[108:111], v[154:157], v[200:203], v[108:111]
	v_mfma_f32_16x16x32_bf16 v[104:107], v[162:165], v[200:203], v[104:107]
	v_mfma_f32_16x16x32_bf16 v[92:95], v[154:157], v[208:211], v[92:95]
	v_mfma_f32_16x16x32_bf16 v[88:91], v[162:165], v[208:211], v[88:91]
	v_mfma_f32_16x16x32_bf16 v[76:79], v[154:157], v[216:219], v[76:79]
	v_mfma_f32_16x16x32_bf16 v[72:75], v[162:165], v[216:219], v[72:75]
	s_setprio 0
	s_setprio 1
	v_mfma_f32_16x16x32_bf16 v[116:119], v[166:169], v[188:191], 0
	v_mfma_f32_16x16x32_bf16 v[112:115], v[174:177], v[188:191], 0
	v_mfma_f32_16x16x32_bf16 v[100:103], v[166:169], v[196:199], 0
	v_mfma_f32_16x16x32_bf16 v[96:99], v[174:177], v[196:199], 0
	v_mfma_f32_16x16x32_bf16 v[84:87], v[166:169], v[204:207], 0
	v_mfma_f32_16x16x32_bf16 v[80:83], v[174:177], v[204:207], 0
	v_mfma_f32_16x16x32_bf16 v[68:71], v[166:169], v[212:215], 0
	v_mfma_f32_16x16x32_bf16 v[64:67], v[174:177], v[212:215], 0
	v_mfma_f32_16x16x32_bf16 v[116:119], v[170:173], v[192:195], v[116:119]
	v_mfma_f32_16x16x32_bf16 v[112:115], v[178:181], v[192:195], v[112:115]
	v_mfma_f32_16x16x32_bf16 v[100:103], v[170:173], v[200:203], v[100:103]
	v_mfma_f32_16x16x32_bf16 v[96:99], v[178:181], v[200:203], v[96:99]
	v_mfma_f32_16x16x32_bf16 v[84:87], v[170:173], v[208:211], v[84:87]
	v_mfma_f32_16x16x32_bf16 v[80:83], v[178:181], v[208:211], v[80:83]
	v_mfma_f32_16x16x32_bf16 v[68:71], v[170:173], v[216:219], v[68:71]
	v_mfma_f32_16x16x32_bf16 v[64:67], v[178:181], v[216:219], v[64:67]
	s_setprio 0
	s_barrier
	s_add_i32 s62, s55, s40
	v_lshl_add_u64 v[220:221], s[36:37], 0, v[130:131]
	s_mov_b32 m0, s62
	ds_read_b128 v[188:191], v153 offset:16384
	ds_read_b128 v[192:195], v153 offset:17408
	ds_read_b128 v[196:199], v153 offset:18432
	ds_read_b128 v[200:203], v153 offset:19456
	ds_read_b128 v[204:207], v153 offset:20480
	ds_read_b128 v[208:211], v153 offset:21504
	ds_read_b128 v[212:215], v153 offset:22528
	ds_read_b128 v[216:219], v153 offset:23552
	global_load_lds_dwordx4 v[220:221], off
	s_add_i32 m0, s62, 0x2000
	s_add_u32 s62, s36, 0x40000
	v_lshl_add_u64 v[222:223], s[36:37], 0, v[134:135]
	s_addc_u32 s63, s37, 0
	s_add_i32 s64, s56, s40
	global_load_lds_dwordx4 v[222:223], off
	v_lshl_add_u64 v[224:225], s[62:63], 0, v[130:131]
	s_mov_b32 m0, s64
	v_lshl_add_u64 v[226:227], s[38:39], 0, v[132:133]
	global_load_lds_dwordx4 v[224:225], off
	v_lshl_add_u64 v[224:225], s[62:63], 0, v[134:135]
	s_add_i32 m0, s64, 0x2000
	s_nop 0
	global_load_lds_dwordx4 v[224:225], off
	v_lshl_add_u64 v[224:225], s[38:39], 0, v[128:129]
	s_mov_b32 m0, s41
	s_nop 0
	global_load_lds_dwordx4 v[224:225], off
	s_mov_b32 m0, s42
	s_nop 0
	global_load_lds_dwordx4 v[226:227], off
	s_waitcnt vmcnt(8)
	s_waitcnt lgkmcnt(0)
	s_barrier
; #define PG8_STAGE(bufoff, gbase, voff) do { _Pragma("unroll") for (int _i = 0; _i < 2; ++_i) \
;         __builtin_amdgcn_global_load_lds((const unsigned*)((const char*)(gbase) + (voff)[_i]), (PG8_LAS unsigned*)(lds + (bufoff) + ldsw + _i * 8192), 16, 0, 0); } while (0)
; #define PG8_LDA(dst, b, h) do { _Pragma("unroll") for (int m = 0; m < 4; ++m) _Pragma("unroll") for (int k = 0; k < 2; ++k) dst[m][k] = *(const PG8_LAS bf16x8*)(lds + PG8_SA(b, h) + aoff + m * 2048 + k * 1024); } while (0)
; #define PG8_LDB(dst, b, h) do { _Pragma("unroll") for (int n = 0; n < 2; ++n) _Pragma("unroll") for (int k = 0; k < 2; ++k) dst[n][k] = *(const PG8_LAS bf16x8*)(lds + PG8_SB(b, h) + boff + n * 2048 + k * 1024); } while (0)
; #define PG8_MMA(ai, bj, At, Bt) do { __builtin_amdgcn_s_setprio(1); _Pragma("unroll") for (int m = 0; m < 4; ++m) _Pragma("unroll") for (int n = 0; n < 2; ++n) _Pragma("unroll") for (int k = 0; k < 2; ++k) \
;         acc[ai][bj][m][n] = __builtin_amdgcn_mfma_f32_16x16x32_bf16(Bt[n][k], At[m][k], acc[ai][bj][m][n], 0, 0, 0); __builtin_amdgcn_s_setprio(0); } while (0)
; #define PG8_WAIT_V(n) asm volatile("s_waitcnt vmcnt(" #n ")" ::: "memory")
; #define PG8_WAIT_L(n) asm volatile("s_waitcnt lgkmcnt(" #n ")" ::: "memory")
; #define PG8_BAR __builtin_amdgcn_s_barrier()
; #define PG8_SCHED __builtin_amdgcn_sched_barrier(0)
; template <class Epi, class Sched, bool ALIGN_EPI = false, bool SP2 = false>
; __device__ __forceinline__ void gemm_phase(PG8_LAS unsigned char* lds, const Gemm g, const Sched& S, const Epi& E) {
;     ...
;             PG8_LDB(B0, 0, 0); PG8_LDB(B1, 0, 1); PG8_SCHED; PG8_LDA(At, 0, 0); PG8_STAGE(PG8_SA(1, 1), a1 + hstep, voffA);
;             PG8_WAIT_V(8); PG8_WAIT_L(0); PG8_BAR; PG8_MMA(0, 0, At, B0); PG8_MMA(0, 1, At, B1); PG8_BAR; PG8_SCHED;
;             PG8_LDA(At, 0, 1); PG8_STAGE(PG8_SB(0, 0), b2, voffB); PG8_STAGE(PG8_SB(0, 1), b2 + hstep, voffB); PG8_STAGE(PG8_SA(0, 0), a2, voffA);
;             PG8_WAIT_V(8); PG8_WAIT_L(0); PG8_BAR; PG8_MMA(1, 0, At, B0); PG8_MMA(1, 1, At, B1); PG8_BAR; PG8_SCHED;
;             PG8_LDB(B0, 1, 0); PG8_LDB(B1, 1, 1); PG8_SCHED; PG8_LDA(At, 1, 0); PG8_STAGE(PG8_SA(0, 1), a2 + hstep, voffA);
;             PG8_WAIT_V(8); PG8_WAIT_L(0); PG8_BAR; PG8_MMA(0, 0, At, B0); PG8_MMA(0, 1, At, B1); PG8_BAR; PG8_SCHED;
	s_setprio 1
	s_waitcnt lgkmcnt(0)
	v_mfma_f32_16x16x32_bf16 v[60:63], v[144:147], v[188:191], 0
	v_mfma_f32_16x16x32_bf16 v[56:59], v[158:161], v[188:191], 0
	v_mfma_f32_16x16x32_bf16 v[44:47], v[144:147], v[196:199], 0
	v_mfma_f32_16x16x32_bf16 v[40:43], v[158:161], v[196:199], 0
	v_mfma_f32_16x16x32_bf16 v[28:31], v[144:147], v[204:207], 0
	v_mfma_f32_16x16x32_bf16 v[24:27], v[158:161], v[204:207], 0
	v_mfma_f32_16x16x32_bf16 v[12:15], v[144:147], v[212:215], 0
	v_mfma_f32_16x16x32_bf16 v[8:11], v[158:161], v[212:215], 0
	v_mfma_f32_16x16x32_bf16 v[60:63], v[154:157], v[192:195], v[60:63]
	v_mfma_f32_16x16x32_bf16 v[56:59], v[162:165], v[192:195], v[56:59]
	v_mfma_f32_16x16x32_bf16 v[44:47], v[154:157], v[200:203], v[44:47]
	v_mfma_f32_16x16x32_bf16 v[40:43], v[162:165], v[200:203], v[40:43]
	v_mfma_f32_16x16x32_bf16 v[28:31], v[154:157], v[208:211], v[28:31]
	v_mfma_f32_16x16x32_bf16 v[24:27], v[162:165], v[208:211], v[24:27]
	v_mfma_f32_16x16x32_bf16 v[12:15], v[154:157], v[216:219], v[12:15]
	v_mfma_f32_16x16x32_bf16 v[8:11], v[162:165], v[216:219], v[8:11]
	s_setprio 0
	s_setprio 1
	v_mfma_f32_16x16x32_bf16 v[52:55], v[166:169], v[188:191], 0
	v_mfma_f32_16x16x32_bf16 v[48:51], v[174:177], v[188:191], 0
	v_mfma_f32_16x16x32_bf16 v[36:39], v[166:169], v[196:199], 0
	v_mfma_f32_16x16x32_bf16 v[32:35], v[174:177], v[196:199], 0
	v_mfma_f32_16x16x32_bf16 v[20:23], v[166:169], v[204:207], 0
	v_mfma_f32_16x16x32_bf16 v[16:19], v[174:177], v[204:207], 0
	v_mfma_f32_16x16x32_bf16 v[4:7], v[166:169], v[212:215], 0
	v_mfma_f32_16x16x32_bf16 v[0:3], v[174:177], v[212:215], 0
	v_mfma_f32_16x16x32_bf16 v[52:55], v[170:173], v[192:195], v[52:55]
	v_mfma_f32_16x16x32_bf16 v[48:51], v[178:181], v[192:195], v[48:51]
	v_mfma_f32_16x16x32_bf16 v[36:39], v[170:173], v[200:203], v[36:39]
	v_mfma_f32_16x16x32_bf16 v[32:35], v[178:181], v[200:203], v[32:35]
	v_mfma_f32_16x16x32_bf16 v[20:23], v[170:173], v[208:211], v[20:23]
	v_mfma_f32_16x16x32_bf16 v[16:19], v[178:181], v[208:211], v[16:19]
	v_mfma_f32_16x16x32_bf16 v[4:7], v[170:173], v[216:219], v[4:7]
	v_mfma_f32_16x16x32_bf16 v[0:3], v[178:181], v[216:219], v[0:3]
	s_setprio 0
	s_barrier
	s_add_i32 s62, 0, 0x18000
	s_add_i32 s63, 0, 0x1c000
	v_add_u32_e32 v162, s62, v149
	v_add_u32_e32 v178, s63, v149
	ds_read_b128 v[144:147], v162
	ds_read_b128 v[154:157], v162 offset:1024
	ds_read_b128 v[158:161], v162 offset:2048
	ds_read_b128 v[162:165], v162 offset:3072
	ds_read_b128 v[166:169], v178
	ds_read_b128 v[170:173], v178 offset:1024
	ds_read_b128 v[174:177], v178 offset:2048
	ds_read_b128 v[178:181], v178 offset:3072
	s_add_u32 s38, s38, 0x40000
	s_addc_u32 s39, s39, 0
	s_mov_b32 m0, s43
	v_lshl_add_u64 v[228:229], s[38:39], 0, v[128:129]
	ds_read_b128 v[188:191], v153 offset:32768
	ds_read_b128 v[192:195], v153 offset:33792
	ds_read_b128 v[196:199], v153 offset:34816
	ds_read_b128 v[200:203], v153 offset:35840
	ds_read_b128 v[204:207], v153 offset:36864
	ds_read_b128 v[208:211], v153 offset:37888
	ds_read_b128 v[212:215], v153 offset:38912
	ds_read_b128 v[216:219], v153 offset:39936
	global_load_lds_dwordx4 v[228:229], off
	v_lshl_add_u64 v[228:229], s[38:39], 0, v[132:133]
	s_mov_b32 m0, s44
	s_nop 0
	global_load_lds_dwordx4 v[228:229], off
	s_waitcnt vmcnt(8)
	s_waitcnt lgkmcnt(0)
	s_barrier
	s_setprio 1
	s_waitcnt lgkmcnt(0)
	v_mfma_f32_16x16x32_bf16 v[124:127], v[144:147], v[188:191], v[124:127]
	v_mfma_f32_16x16x32_bf16 v[120:123], v[158:161], v[188:191], v[120:123]
	v_mfma_f32_16x16x32_bf16 v[108:111], v[144:147], v[196:199], v[108:111]
	v_mfma_f32_16x16x32_bf16 v[104:107], v[158:161], v[196:199], v[104:107]
	v_mfma_f32_16x16x32_bf16 v[92:95], v[144:147], v[204:207], v[92:95]
	v_mfma_f32_16x16x32_bf16 v[88:91], v[158:161], v[204:207], v[88:91]
	v_mfma_f32_16x16x32_bf16 v[76:79], v[144:147], v[212:215], v[76:79]
	v_mfma_f32_16x16x32_bf16 v[72:75], v[158:161], v[212:215], v[72:75]
	v_mfma_f32_16x16x32_bf16 v[124:127], v[154:157], v[192:195], v[124:127]
	v_mfma_f32_16x16x32_bf16 v[120:123], v[162:165], v[192:195], v[120:123]
	v_mfma_f32_16x16x32_bf16 v[108:111], v[154:157], v[200:203], v[108:111]
	v_mfma_f32_16x16x32_bf16 v[104:107], v[162:165], v[200:203], v[104:107]
	v_mfma_f32_16x16x32_bf16 v[92:95], v[154:157], v[208:211], v[92:95]
	v_mfma_f32_16x16x32_bf16 v[88:91], v[162:165], v[208:211], v[88:91]
	v_mfma_f32_16x16x32_bf16 v[76:79], v[154:157], v[216:219], v[76:79]
	v_mfma_f32_16x16x32_bf16 v[72:75], v[162:165], v[216:219], v[72:75]
	s_setprio 0
	s_setprio 1
	v_mfma_f32_16x16x32_bf16 v[116:119], v[166:169], v[188:191], v[116:119]
	v_mfma_f32_16x16x32_bf16 v[112:115], v[174:177], v[188:191], v[112:115]
	v_mfma_f32_16x16x32_bf16 v[100:103], v[166:169], v[196:199], v[100:103]
	v_mfma_f32_16x16x32_bf16 v[96:99], v[174:177], v[196:199], v[96:99]
	v_mfma_f32_16x16x32_bf16 v[84:87], v[166:169], v[204:207], v[84:87]
	v_mfma_f32_16x16x32_bf16 v[80:83], v[174:177], v[204:207], v[80:83]
	v_mfma_f32_16x16x32_bf16 v[68:71], v[166:169], v[212:215], v[68:71]
	v_mfma_f32_16x16x32_bf16 v[64:67], v[174:177], v[212:215], v[64:67]
	v_mfma_f32_16x16x32_bf16 v[116:119], v[170:173], v[192:195], v[116:119]
	v_mfma_f32_16x16x32_bf16 v[112:115], v[178:181], v[192:195], v[112:115]
	v_mfma_f32_16x16x32_bf16 v[100:103], v[170:173], v[200:203], v[100:103]
	v_mfma_f32_16x16x32_bf16 v[96:99], v[178:181], v[200:203], v[96:99]
	v_mfma_f32_16x16x32_bf16 v[84:87], v[170:173], v[208:211], v[84:87]
	v_mfma_f32_16x16x32_bf16 v[80:83], v[178:181], v[208:211], v[80:83]
	v_mfma_f32_16x16x32_bf16 v[68:71], v[170:173], v[216:219], v[68:71]
	v_mfma_f32_16x16x32_bf16 v[64:67], v[178:181], v[216:219], v[64:67]
	s_setprio 0
	s_barrier
; #define PG8_STAGE(bufoff, gbase, voff) do { _Pragma("unroll") for (int _i = 0; _i < 2; ++_i) \
;         __builtin_amdgcn_global_load_lds((const unsigned*)((const char*)(gbase) + (voff)[_i]), (PG8_LAS unsigned*)(lds + (bufoff) + ldsw + _i * 8192), 16, 0, 0); } while (0)
; #define PG8_LDA(dst, b, h) do { _Pragma("unroll") for (int m = 0; m < 4; ++m) _Pragma("unroll") for (int k = 0; k < 2; ++k) dst[m][k] = *(const PG8_LAS bf16x8*)(lds + PG8_SA(b, h) + aoff + m * 2048 + k * 1024); } while (0)
; #define PG8_LDB(dst, b, h) do { _Pragma("unroll") for (int n = 0; n < 2; ++n) _Pragma("unroll") for (int k = 0; k < 2; ++k) dst[n][k] = *(const PG8_LAS bf16x8*)(lds + PG8_SB(b, h) + boff + n * 2048 + k * 1024); } while (0)
; #define PG8_MMA(ai, bj, At, Bt) do { __builtin_amdgcn_s_setprio(1); _Pragma("unroll") for (int m = 0; m < 4; ++m) _Pragma("unroll") for (int n = 0; n < 2; ++n) _Pragma("unroll") for (int k = 0; k < 2; ++k) \
;         acc[ai][bj][m][n] = __builtin_amdgcn_mfma_f32_16x16x32_bf16(Bt[n][k], At[m][k], acc[ai][bj][m][n], 0, 0, 0); __builtin_amdgcn_s_setprio(0); } while (0)
; #define PG8_WAIT_V(n) asm volatile("s_waitcnt vmcnt(" #n ")" ::: "memory")
; #define PG8_WAIT_L(n) asm volatile("s_waitcnt lgkmcnt(" #n ")" ::: "memory")
; #define PG8_BAR __builtin_amdgcn_s_barrier()
; #define PG8_SCHED __builtin_amdgcn_sched_barrier(0)
; template <class Epi, class Sched, bool ALIGN_EPI = false, bool SP2 = false>
; __device__ __forceinline__ void gemm_phase(PG8_LAS unsigned char* lds, const Gemm g, const Sched& S, const Epi& E) {
;     ...
;         for (int t = 0; t < nt; t += 2) {
;     ...
;             PG8_LDB(B0, 1, 0); PG8_LDB(B1, 1, 1); PG8_SCHED; PG8_LDA(At, 1, 0); PG8_STAGE(PG8_SA(0, 1), a2 + hstep, voffA);
;             PG8_WAIT_V(8); PG8_WAIT_L(0); PG8_BAR; PG8_MMA(0, 0, At, B0); PG8_MMA(0, 1, At, B1); PG8_BAR; PG8_SCHED;
;             PG8_LDA(At, 1, 1); PG8_STAGE(PG8_SB(1, 0), b3, voffB); PG8_STAGE(PG8_SB(1, 1), b3 + hstep, voffB); PG8_STAGE(PG8_SA(1, 0), a3, voffA);
;             PG8_WAIT_V(8); PG8_WAIT_L(0); PG8_BAR; PG8_MMA(1, 0, At, B0); PG8_MMA(1, 1, At, B1); PG8_BAR; PG8_SCHED;
	s_add_i32 s38, s62, s40
	v_lshl_add_u64 v[220:221], v[220:221], 0, s[16:17]
	s_mov_b32 m0, s38
	ds_read_b128 v[188:191], v153 offset:49152
	ds_read_b128 v[192:195], v153 offset:50176
	ds_read_b128 v[196:199], v153 offset:51200
	ds_read_b128 v[200:203], v153 offset:52224
	ds_read_b128 v[204:207], v153 offset:53248
	ds_read_b128 v[208:211], v153 offset:54272
	ds_read_b128 v[212:215], v153 offset:55296
	ds_read_b128 v[216:219], v153 offset:56320
	global_load_lds_dwordx4 v[220:221], off
	s_add_i32 m0, s38, 0x2000
	s_add_u32 s36, s36, 0x40080
	v_lshl_add_u64 v[220:221], v[222:223], 0, s[16:17]
	s_addc_u32 s37, s37, 0
	s_add_i32 s38, s63, s40
	global_load_lds_dwordx4 v[220:221], off
	v_lshl_add_u64 v[220:221], s[36:37], 0, v[130:131]
	s_mov_b32 m0, s38
	s_nop 0
	global_load_lds_dwordx4 v[220:221], off
	v_lshl_add_u64 v[220:221], s[36:37], 0, v[134:135]
	s_add_i32 m0, s38, 0x2000
	s_nop 0
	global_load_lds_dwordx4 v[220:221], off
	v_lshl_add_u64 v[220:221], v[224:225], 0, s[16:17]
	s_mov_b32 m0, s46
	s_nop 0
	global_load_lds_dwordx4 v[220:221], off
	v_lshl_add_u64 v[220:221], v[226:227], 0, s[16:17]
	s_mov_b32 m0, s47
	s_nop 0
	global_load_lds_dwordx4 v[220:221], off
	s_waitcnt vmcnt(8)
	s_waitcnt lgkmcnt(0)
	s_barrier
	s_setprio 1
	s_waitcnt lgkmcnt(0)
	v_mfma_f32_16x16x32_bf16 v[60:63], v[144:147], v[188:191], v[60:63]
	v_mfma_f32_16x16x32_bf16 v[56:59], v[158:161], v[188:191], v[56:59]
	v_mfma_f32_16x16x32_bf16 v[44:47], v[144:147], v[196:199], v[44:47]
	v_mfma_f32_16x16x32_bf16 v[40:43], v[158:161], v[196:199], v[40:43]
	v_mfma_f32_16x16x32_bf16 v[28:31], v[144:147], v[204:207], v[28:31]
	v_mfma_f32_16x16x32_bf16 v[24:27], v[158:161], v[204:207], v[24:27]
	v_mfma_f32_16x16x32_bf16 v[12:15], v[144:147], v[212:215], v[12:15]
	v_mfma_f32_16x16x32_bf16 v[8:11], v[158:161], v[212:215], v[8:11]
	v_mfma_f32_16x16x32_bf16 v[60:63], v[154:157], v[192:195], v[60:63]
	v_mfma_f32_16x16x32_bf16 v[56:59], v[162:165], v[192:195], v[56:59]
	v_mfma_f32_16x16x32_bf16 v[44:47], v[154:157], v[200:203], v[44:47]
	v_mfma_f32_16x16x32_bf16 v[40:43], v[162:165], v[200:203], v[40:43]
	v_mfma_f32_16x16x32_bf16 v[28:31], v[154:157], v[208:211], v[28:31]
	v_mfma_f32_16x16x32_bf16 v[24:27], v[162:165], v[208:211], v[24:27]
	v_mfma_f32_16x16x32_bf16 v[12:15], v[154:157], v[216:219], v[12:15]
	v_mfma_f32_16x16x32_bf16 v[8:11], v[162:165], v[216:219], v[8:11]
	s_setprio 0
	s_setprio 1
	v_mfma_f32_16x16x32_bf16 v[52:55], v[166:169], v[188:191], v[52:55]
	v_mfma_f32_16x16x32_bf16 v[48:51], v[174:177], v[188:191], v[48:51]
	v_mfma_f32_16x16x32_bf16 v[36:39], v[166:169], v[196:199], v[36:39]
	v_mfma_f32_16x16x32_bf16 v[32:35], v[174:177], v[196:199], v[32:35]
	v_mfma_f32_16x16x32_bf16 v[20:23], v[166:169], v[204:207], v[20:23]
	v_mfma_f32_16x16x32_bf16 v[16:19], v[174:177], v[204:207], v[16:19]
	v_mfma_f32_16x16x32_bf16 v[4:7], v[166:169], v[212:215], v[4:7]
	v_mfma_f32_16x16x32_bf16 v[0:3], v[174:177], v[212:215], v[0:3]
	v_mfma_f32_16x16x32_bf16 v[52:55], v[170:173], v[192:195], v[52:55]
	v_mfma_f32_16x16x32_bf16 v[48:51], v[178:181], v[192:195], v[48:51]
	v_mfma_f32_16x16x32_bf16 v[36:39], v[170:173], v[200:203], v[36:39]
	v_mfma_f32_16x16x32_bf16 v[32:35], v[178:181], v[200:203], v[32:35]
	v_mfma_f32_16x16x32_bf16 v[20:23], v[170:173], v[208:211], v[20:23]
	v_mfma_f32_16x16x32_bf16 v[16:19], v[178:181], v[208:211], v[16:19]
	v_mfma_f32_16x16x32_bf16 v[4:7], v[170:173], v[216:219], v[4:7]
	v_mfma_f32_16x16x32_bf16 v[0:3], v[178:181], v[216:219], v[0:3]
	s_setprio 0
	s_barrier
	s_add_i32 s61, s61, 2
	s_add_u32 s30, s30, 0x100
	s_addc_u32 s31, s31, 0
	s_add_u32 s59, s59, 0x100
	s_addc_u32 s60, s60, 0
	s_cmp_gt_u32 s61, 13

; #define PG8_STAGE(bufoff, gbase, voff) do { _Pragma("unroll") for (int _i = 0; _i < 2; ++_i) \
;         __builtin_amdgcn_global_load_lds((const unsigned*)((const char*)(gbase) + (voff)[_i]), (PG8_LAS unsigned*)(lds + (bufoff) + ldsw + _i * 8192), 16, 0, 0); } while (0)
; #define PG8_LDA(dst, b, h) do { _Pragma("unroll") for (int m = 0; m < 4; ++m) _Pragma("unroll") for (int k = 0; k < 2; ++k) dst[m][k] = *(const PG8_LAS bf16x8*)(lds + PG8_SA(b, h) + aoff + m * 2048 + k * 1024); } while (0)
; #define PG8_LDB(dst, b, h) do { _Pragma("unroll") for (int n = 0; n < 2; ++n) _Pragma("unroll") for (int k = 0; k < 2; ++k) dst[n][k] = *(const PG8_LAS bf16x8*)(lds + PG8_SB(b, h) + boff + n * 2048 + k * 1024); } while (0)
; #define PG8_MMA(ai, bj, At, Bt) do { __builtin_amdgcn_s_setprio(1); _Pragma("unroll") for (int m = 0; m < 4; ++m) _Pragma("unroll") for (int n = 0; n < 2; ++n) _Pragma("unroll") for (int k = 0; k < 2; ++k) \
;         acc[ai][bj][m][n] = __builtin_amdgcn_mfma_f32_16x16x32_bf16(Bt[n][k], At[m][k], acc[ai][bj][m][n], 0, 0, 0); __builtin_amdgcn_s_setprio(0); } while (0)
; #define PG8_WAIT_V(n) asm volatile("s_waitcnt vmcnt(" #n ")" ::: "memory")
; #define PG8_WAIT_L(n) asm volatile("s_waitcnt lgkmcnt(" #n ")" ::: "memory")
; #define PG8_BAR __builtin_amdgcn_s_barrier()
; #define PG8_SCHED __builtin_amdgcn_sched_barrier(0)
; template <class Epi, class Sched, bool ALIGN_EPI = false, bool SP2 = false>
; __device__ __forceinline__ void gemm_phase(PG8_LAS unsigned char* lds, const Gemm g, const Sched& S, const Epi& E) {
;     ...
;     f32x4 acc[2][2][4][2];
; #pragma unroll
;     for (int a = 0; a < 2; ++a)
; #pragma unroll
;         for (int b = 0; b < 2; ++b)
; #pragma unroll
;             for (int m = 0; m < 4; ++m)
; #pragma unroll
;                 for (int n = 0; n < 2; ++n) acc[a][b][m][n] = (f32x4){0.f, 0.f, 0.f, 0.f};
;     ...
;             PG8_LDB(B0, 0, 0); PG8_LDB(B1, 0, 1); PG8_SCHED; PG8_LDA(At, 0, 0); PG8_STAGE(PG8_SA(1, 1), a1 + hstep, voffA);
;             PG8_WAIT_V(8); PG8_WAIT_L(0); PG8_BAR; PG8_MMA(0, 0, At, B0); PG8_MMA(0, 1, At, B1); PG8_BAR; PG8_SCHED;
;             PG8_LDA(At, 0, 1); PG8_STAGE(PG8_SB(0, 0), b2, voffB); PG8_STAGE(PG8_SB(0, 1), b2 + hstep, voffB); PG8_STAGE(PG8_SA(0, 0), a2, voffA);
.LBB0_859:
	s_ashr_i32 s19, s18, 31
	s_lshl_b64 s[20:21], s[18:19], 19
	s_add_u32 s20, s50, s20
	s_addc_u32 s21, s51, s21
	s_and_b64 s[22:23], s[6:7], exec
	s_cselect_b32 s19, s21, s27
	s_cselect_b32 s54, s20, s26
	s_ashr_i32 s17, s16, 31
	s_lshl_b64 s[22:23], s[16:17], 19
	s_add_u32 s22, s33, s22
	s_addc_u32 s23, s34, s23
	s_and_b64 s[30:31], s[6:7], exec
	s_cselect_b32 s17, s23, s29
	s_cselect_b32 s55, s22, s28
	s_add_u32 s26, s26, 0x40080
	s_addc_u32 s27, s27, 0
	s_add_u32 s56, s28, 0x100
	s_addc_u32 s57, s29, 0
	s_mov_b32 s58, -2
	s_waitcnt vmcnt(0)
	ds_read_b128 v[146:149], v152
	ds_read_b128 v[156:159], v152 offset:1024
	ds_read_b128 v[160:163], v152 offset:2048
	ds_read_b128 v[164:167], v152 offset:3072
	ds_read_b128 v[168:171], v153
	ds_read_b128 v[172:175], v153 offset:1024
	ds_read_b128 v[176:179], v153 offset:2048
	ds_read_b128 v[186:189], v153 offset:3072
	s_add_u32 s28, s26, 0xfffc0080
	s_addc_u32 s29, s27, -1
	s_cmp_eq_u32 s58, 12
	s_cselect_b32 s31, s19, s29
	s_cselect_b32 s30, s54, s28
	s_cselect_b32 s29, s17, s57
	s_cselect_b32 s28, s55, s56
	v_lshl_add_u64 v[180:181], s[26:27], 0, v[138:139]
	s_add_i32 m0, s38, 0xc000
	ds_read_b128 v[190:193], v154
	ds_read_b128 v[194:197], v154 offset:1024
	ds_read_b128 v[198:201], v154 offset:2048
	ds_read_b128 v[202:205], v154 offset:3072
	ds_read_b128 v[206:209], v154 offset:4096
	ds_read_b128 v[210:213], v154 offset:5120
	ds_read_b128 v[214:217], v154 offset:6144
	ds_read_b128 v[218:221], v154 offset:7168
	global_load_lds_dwordx4 v[180:181], off
	v_lshl_add_u64 v[180:181], s[26:27], 0, v[140:141]
	s_add_i32 m0, s38, 0xe000
	s_nop 0
	global_load_lds_dwordx4 v[180:181], off
	s_waitcnt vmcnt(8)
	s_waitcnt lgkmcnt(0)
	s_barrier
	s_setprio 1
	s_waitcnt lgkmcnt(0)
	v_mfma_f32_16x16x32_bf16 v[124:127], v[146:149], v[190:193], 0
	v_mfma_f32_16x16x32_bf16 v[120:123], v[160:163], v[190:193], 0
	v_mfma_f32_16x16x32_bf16 v[108:111], v[146:149], v[198:201], 0
	v_mfma_f32_16x16x32_bf16 v[104:107], v[160:163], v[198:201], 0
	v_mfma_f32_16x16x32_bf16 v[92:95], v[146:149], v[206:209], 0
	v_mfma_f32_16x16x32_bf16 v[88:91], v[160:163], v[206:209], 0
	v_mfma_f32_16x16x32_bf16 v[76:79], v[146:149], v[214:217], 0
	v_mfma_f32_16x16x32_bf16 v[72:75], v[160:163], v[214:217], 0
	v_mfma_f32_16x16x32_bf16 v[124:127], v[156:159], v[194:197], v[124:127]
	v_mfma_f32_16x16x32_bf16 v[120:123], v[164:167], v[194:197], v[120:123]
	v_mfma_f32_16x16x32_bf16 v[108:111], v[156:159], v[202:205], v[108:111]
	v_mfma_f32_16x16x32_bf16 v[104:107], v[164:167], v[202:205], v[104:107]
	v_mfma_f32_16x16x32_bf16 v[92:95], v[156:159], v[210:213], v[92:95]
	v_mfma_f32_16x16x32_bf16 v[88:91], v[164:167], v[210:213], v[88:91]
	v_mfma_f32_16x16x32_bf16 v[76:79], v[156:159], v[218:221], v[76:79]
	v_mfma_f32_16x16x32_bf16 v[72:75], v[164:167], v[218:221], v[72:75]
	s_setprio 0
	s_setprio 1
	v_mfma_f32_16x16x32_bf16 v[116:119], v[168:171], v[190:193], 0
	v_mfma_f32_16x16x32_bf16 v[112:115], v[176:179], v[190:193], 0
	v_mfma_f32_16x16x32_bf16 v[100:103], v[168:171], v[198:201], 0
	v_mfma_f32_16x16x32_bf16 v[96:99], v[176:179], v[198:201], 0
	v_mfma_f32_16x16x32_bf16 v[84:87], v[168:171], v[206:209], 0
	v_mfma_f32_16x16x32_bf16 v[80:83], v[176:179], v[206:209], 0
	v_mfma_f32_16x16x32_bf16 v[68:71], v[168:171], v[214:217], 0
	v_mfma_f32_16x16x32_bf16 v[64:67], v[176:179], v[214:217], 0
	v_mfma_f32_16x16x32_bf16 v[116:119], v[172:175], v[194:197], v[116:119]
	v_mfma_f32_16x16x32_bf16 v[112:115], v[186:189], v[194:197], v[112:115]
	v_mfma_f32_16x16x32_bf16 v[100:103], v[172:175], v[202:205], v[100:103]
	v_mfma_f32_16x16x32_bf16 v[96:99], v[186:189], v[202:205], v[96:99]
	v_mfma_f32_16x16x32_bf16 v[84:87], v[172:175], v[210:213], v[84:87]
	v_mfma_f32_16x16x32_bf16 v[80:83], v[186:189], v[210:213], v[80:83]
	v_mfma_f32_16x16x32_bf16 v[68:71], v[172:175], v[218:221], v[68:71]
	v_mfma_f32_16x16x32_bf16 v[64:67], v[186:189], v[218:221], v[64:67]
	s_setprio 0
	s_barrier
	s_add_i32 s59, s45, s35
	v_lshl_add_u64 v[180:181], s[28:29], 0, v[132:133]
	s_mov_b32 m0, s59
	ds_read_b128 v[190:193], v154 offset:16384
	ds_read_b128 v[194:197], v154 offset:17408
	ds_read_b128 v[198:201], v154 offset:18432
	ds_read_b128 v[202:205], v154 offset:19456
	ds_read_b128 v[206:209], v154 offset:20480
	ds_read_b128 v[210:213], v154 offset:21504
	ds_read_b128 v[214:217], v154 offset:22528
	ds_read_b128 v[218:221], v154 offset:23552
	global_load_lds_dwordx4 v[180:181], off
	s_add_i32 m0, s59, 0x2000
	s_add_u32 s60, s28, 0x40000
	v_lshl_add_u64 v[222:223], s[28:29], 0, v[128:129]
	s_addc_u32 s61, s29, 0
	s_add_i32 s59, s46, s35
	global_load_lds_dwordx4 v[222:223], off
	v_lshl_add_u64 v[224:225], s[60:61], 0, v[132:133]
	s_mov_b32 m0, s59
	v_lshl_add_u64 v[226:227], s[30:31], 0, v[130:131]
	global_load_lds_dwordx4 v[224:225], off
	v_lshl_add_u64 v[224:225], s[60:61], 0, v[128:129]
	s_add_i32 m0, s59, 0x2000
	s_nop 0
	global_load_lds_dwordx4 v[224:225], off
	v_lshl_add_u64 v[224:225], s[30:31], 0, v[134:135]
	s_mov_b32 m0, s38
	s_nop 0
	global_load_lds_dwordx4 v[224:225], off
	s_mov_b32 m0, s39
	s_nop 0
	global_load_lds_dwordx4 v[226:227], off
	s_waitcnt vmcnt(8)
	s_waitcnt lgkmcnt(0)
	s_barrier
; #define PG8_STAGE(bufoff, gbase, voff) do { _Pragma("unroll") for (int _i = 0; _i < 2; ++_i) \
;         __builtin_amdgcn_global_load_lds((const unsigned*)((const char*)(gbase) + (voff)[_i]), (PG8_LAS unsigned*)(lds + (bufoff) + ldsw + _i * 8192), 16, 0, 0); } while (0)
; #define PG8_LDA(dst, b, h) do { _Pragma("unroll") for (int m = 0; m < 4; ++m) _Pragma("unroll") for (int k = 0; k < 2; ++k) dst[m][k] = *(const PG8_LAS bf16x8*)(lds + PG8_SA(b, h) + aoff + m * 2048 + k * 1024); } while (0)
; #define PG8_LDB(dst, b, h) do { _Pragma("unroll") for (int n = 0; n < 2; ++n) _Pragma("unroll") for (int k = 0; k < 2; ++k) dst[n][k] = *(const PG8_LAS bf16x8*)(lds + PG8_SB(b, h) + boff + n * 2048 + k * 1024); } while (0)
; #define PG8_MMA(ai, bj, At, Bt) do { __builtin_amdgcn_s_setprio(1); _Pragma("unroll") for (int m = 0; m < 4; ++m) _Pragma("unroll") for (int n = 0; n < 2; ++n) _Pragma("unroll") for (int k = 0; k < 2; ++k) \
;         acc[ai][bj][m][n] = __builtin_amdgcn_mfma_f32_16x16x32_bf16(Bt[n][k], At[m][k], acc[ai][bj][m][n], 0, 0, 0); __builtin_amdgcn_s_setprio(0); } while (0)
; #define PG8_WAIT_V(n) asm volatile("s_waitcnt vmcnt(" #n ")" ::: "memory")
; #define PG8_WAIT_L(n) asm volatile("s_waitcnt lgkmcnt(" #n ")" ::: "memory")
; #define PG8_BAR __builtin_amdgcn_s_barrier()
; #define PG8_SCHED __builtin_amdgcn_sched_barrier(0)
; template <class Epi, class Sched, bool ALIGN_EPI = false, bool SP2 = false>
; __device__ __forceinline__ void gemm_phase(PG8_LAS unsigned char* lds, const Gemm g, const Sched& S, const Epi& E) {
;     ...
;             PG8_WAIT_V(8); PG8_WAIT_L(0); PG8_BAR; PG8_MMA(1, 0, At, B0); PG8_MMA(1, 1, At, B1); PG8_BAR; PG8_SCHED;
;             PG8_LDB(B0, 1, 0); PG8_LDB(B1, 1, 1); PG8_SCHED; PG8_LDA(At, 1, 0); PG8_STAGE(PG8_SA(0, 1), a2 + hstep, voffA);
;             PG8_WAIT_V(8); PG8_WAIT_L(0); PG8_BAR; PG8_MMA(0, 0, At, B0); PG8_MMA(0, 1, At, B1); PG8_BAR; PG8_SCHED;
	s_setprio 1
	s_waitcnt lgkmcnt(0)
	v_mfma_f32_16x16x32_bf16 v[60:63], v[146:149], v[190:193], 0
	v_mfma_f32_16x16x32_bf16 v[56:59], v[160:163], v[190:193], 0
	v_mfma_f32_16x16x32_bf16 v[44:47], v[146:149], v[198:201], 0
	v_mfma_f32_16x16x32_bf16 v[40:43], v[160:163], v[198:201], 0
	v_mfma_f32_16x16x32_bf16 v[28:31], v[146:149], v[206:209], 0
	v_mfma_f32_16x16x32_bf16 v[24:27], v[160:163], v[206:209], 0
	v_mfma_f32_16x16x32_bf16 v[12:15], v[146:149], v[214:217], 0
	v_mfma_f32_16x16x32_bf16 v[8:11], v[160:163], v[214:217], 0
	v_mfma_f32_16x16x32_bf16 v[60:63], v[156:159], v[194:197], v[60:63]
	v_mfma_f32_16x16x32_bf16 v[56:59], v[164:167], v[194:197], v[56:59]
	v_mfma_f32_16x16x32_bf16 v[44:47], v[156:159], v[202:205], v[44:47]
	v_mfma_f32_16x16x32_bf16 v[40:43], v[164:167], v[202:205], v[40:43]
	v_mfma_f32_16x16x32_bf16 v[28:31], v[156:159], v[210:213], v[28:31]
	v_mfma_f32_16x16x32_bf16 v[24:27], v[164:167], v[210:213], v[24:27]
	v_mfma_f32_16x16x32_bf16 v[12:15], v[156:159], v[218:221], v[12:15]
	v_mfma_f32_16x16x32_bf16 v[8:11], v[164:167], v[218:221], v[8:11]
	s_setprio 0
	s_setprio 1
	v_mfma_f32_16x16x32_bf16 v[52:55], v[168:171], v[190:193], 0
	v_mfma_f32_16x16x32_bf16 v[48:51], v[176:179], v[190:193], 0
	v_mfma_f32_16x16x32_bf16 v[36:39], v[168:171], v[198:201], 0
	v_mfma_f32_16x16x32_bf16 v[32:35], v[176:179], v[198:201], 0
	v_mfma_f32_16x16x32_bf16 v[20:23], v[168:171], v[206:209], 0
	v_mfma_f32_16x16x32_bf16 v[16:19], v[176:179], v[206:209], 0
	v_mfma_f32_16x16x32_bf16 v[4:7], v[168:171], v[214:217], 0
	v_mfma_f32_16x16x32_bf16 v[0:3], v[176:179], v[214:217], 0
	v_mfma_f32_16x16x32_bf16 v[52:55], v[172:175], v[194:197], v[52:55]
	v_mfma_f32_16x16x32_bf16 v[48:51], v[186:189], v[194:197], v[48:51]
	v_mfma_f32_16x16x32_bf16 v[36:39], v[172:175], v[202:205], v[36:39]
	v_mfma_f32_16x16x32_bf16 v[32:35], v[186:189], v[202:205], v[32:35]
	v_mfma_f32_16x16x32_bf16 v[20:23], v[172:175], v[210:213], v[20:23]
	v_mfma_f32_16x16x32_bf16 v[16:19], v[186:189], v[210:213], v[16:19]
	v_mfma_f32_16x16x32_bf16 v[4:7], v[172:175], v[218:221], v[4:7]
	v_mfma_f32_16x16x32_bf16 v[0:3], v[186:189], v[218:221], v[0:3]
	s_setprio 0
	s_barrier
	s_add_i32 s59, 0, 0x18000
	s_add_i32 s60, 0, 0x1c000
	v_add_u32_e32 v164, s59, v151
	v_add_u32_e32 v185, s60, v151
	ds_read_b128 v[146:149], v164
	ds_read_b128 v[156:159], v164 offset:1024
	ds_read_b128 v[160:163], v164 offset:2048
	ds_read_b128 v[164:167], v164 offset:3072
	ds_read_b128 v[168:171], v185
	ds_read_b128 v[172:175], v185 offset:1024
	ds_read_b128 v[176:179], v185 offset:2048
	ds_read_b128 v[186:189], v185 offset:3072
	s_add_u32 s30, s30, 0x40000
	s_addc_u32 s31, s31, 0
	s_mov_b32 m0, s40
	v_lshl_add_u64 v[228:229], s[30:31], 0, v[134:135]
	ds_read_b128 v[190:193], v154 offset:32768
	ds_read_b128 v[194:197], v154 offset:33792
	ds_read_b128 v[198:201], v154 offset:34816
	ds_read_b128 v[202:205], v154 offset:35840
	ds_read_b128 v[206:209], v154 offset:36864
	ds_read_b128 v[210:213], v154 offset:37888
	ds_read_b128 v[214:217], v154 offset:38912
	ds_read_b128 v[218:221], v154 offset:39936
	global_load_lds_dwordx4 v[228:229], off
	v_lshl_add_u64 v[228:229], s[30:31], 0, v[130:131]
	s_mov_b32 m0, s41
	s_nop 0
	global_load_lds_dwordx4 v[228:229], off
	s_waitcnt vmcnt(8)
	s_waitcnt lgkmcnt(0)
	s_barrier
	s_setprio 1
	s_waitcnt lgkmcnt(0)
	v_mfma_f32_16x16x32_bf16 v[124:127], v[146:149], v[190:193], v[124:127]
	v_mfma_f32_16x16x32_bf16 v[120:123], v[160:163], v[190:193], v[120:123]
	v_mfma_f32_16x16x32_bf16 v[108:111], v[146:149], v[198:201], v[108:111]
	v_mfma_f32_16x16x32_bf16 v[104:107], v[160:163], v[198:201], v[104:107]
	v_mfma_f32_16x16x32_bf16 v[92:95], v[146:149], v[206:209], v[92:95]
	v_mfma_f32_16x16x32_bf16 v[88:91], v[160:163], v[206:209], v[88:91]
	v_mfma_f32_16x16x32_bf16 v[76:79], v[146:149], v[214:217], v[76:79]
	v_mfma_f32_16x16x32_bf16 v[72:75], v[160:163], v[214:217], v[72:75]
	v_mfma_f32_16x16x32_bf16 v[124:127], v[156:159], v[194:197], v[124:127]
	v_mfma_f32_16x16x32_bf16 v[120:123], v[164:167], v[194:197], v[120:123]
	v_mfma_f32_16x16x32_bf16 v[108:111], v[156:159], v[202:205], v[108:111]
	v_mfma_f32_16x16x32_bf16 v[104:107], v[164:167], v[202:205], v[104:107]
	v_mfma_f32_16x16x32_bf16 v[92:95], v[156:159], v[210:213], v[92:95]
	v_mfma_f32_16x16x32_bf16 v[88:91], v[164:167], v[210:213], v[88:91]
	v_mfma_f32_16x16x32_bf16 v[76:79], v[156:159], v[218:221], v[76:79]
	v_mfma_f32_16x16x32_bf16 v[72:75], v[164:167], v[218:221], v[72:75]
	s_setprio 0
	s_setprio 1
	v_mfma_f32_16x16x32_bf16 v[116:119], v[168:171], v[190:193], v[116:119]
	v_mfma_f32_16x16x32_bf16 v[112:115], v[176:179], v[190:193], v[112:115]
	v_mfma_f32_16x16x32_bf16 v[100:103], v[168:171], v[198:201], v[100:103]
	v_mfma_f32_16x16x32_bf16 v[96:99], v[176:179], v[198:201], v[96:99]
	v_mfma_f32_16x16x32_bf16 v[84:87], v[168:171], v[206:209], v[84:87]
	v_mfma_f32_16x16x32_bf16 v[80:83], v[176:179], v[206:209], v[80:83]
	v_mfma_f32_16x16x32_bf16 v[68:71], v[168:171], v[214:217], v[68:71]
	v_mfma_f32_16x16x32_bf16 v[64:67], v[176:179], v[214:217], v[64:67]
	v_mfma_f32_16x16x32_bf16 v[116:119], v[172:175], v[194:197], v[116:119]
	v_mfma_f32_16x16x32_bf16 v[112:115], v[186:189], v[194:197], v[112:115]
	v_mfma_f32_16x16x32_bf16 v[100:103], v[172:175], v[202:205], v[100:103]
	v_mfma_f32_16x16x32_bf16 v[96:99], v[186:189], v[202:205], v[96:99]
	v_mfma_f32_16x16x32_bf16 v[84:87], v[172:175], v[210:213], v[84:87]
	v_mfma_f32_16x16x32_bf16 v[80:83], v[186:189], v[210:213], v[80:83]
	v_mfma_f32_16x16x32_bf16 v[68:71], v[172:175], v[218:221], v[68:71]
	v_mfma_f32_16x16x32_bf16 v[64:67], v[186:189], v[218:221], v[64:67]
	s_setprio 0
	s_barrier
; #define PG8_STAGE(bufoff, gbase, voff) do { _Pragma("unroll") for (int _i = 0; _i < 2; ++_i) \
;         __builtin_amdgcn_global_load_lds((const unsigned*)((const char*)(gbase) + (voff)[_i]), (PG8_LAS unsigned*)(lds + (bufoff) + ldsw + _i * 8192), 16, 0, 0); } while (0)
; #define PG8_LDA(dst, b, h) do { _Pragma("unroll") for (int m = 0; m < 4; ++m) _Pragma("unroll") for (int k = 0; k < 2; ++k) dst[m][k] = *(const PG8_LAS bf16x8*)(lds + PG8_SA(b, h) + aoff + m * 2048 + k * 1024); } while (0)
; #define PG8_MMA(ai, bj, At, Bt) do { __builtin_amdgcn_s_setprio(1); _Pragma("unroll") for (int m = 0; m < 4; ++m) _Pragma("unroll") for (int n = 0; n < 2; ++n) _Pragma("unroll") for (int k = 0; k < 2; ++k) \
;         acc[ai][bj][m][n] = __builtin_amdgcn_mfma_f32_16x16x32_bf16(Bt[n][k], At[m][k], acc[ai][bj][m][n], 0, 0, 0); __builtin_amdgcn_s_setprio(0); } while (0)
; #define PG8_WAIT_V(n) asm volatile("s_waitcnt vmcnt(" #n ")" ::: "memory")
; #define PG8_WAIT_L(n) asm volatile("s_waitcnt lgkmcnt(" #n ")" ::: "memory")
; #define PG8_BAR __builtin_amdgcn_s_barrier()
; #define PG8_SCHED __builtin_amdgcn_sched_barrier(0)
; template <class Epi, class Sched, bool ALIGN_EPI = false, bool SP2 = false>
; __device__ __forceinline__ void gemm_phase(PG8_LAS unsigned char* lds, const Gemm g, const Sched& S, const Epi& E) {
;     ...
;         for (int t = 0; t < nt; t += 2) {
;     ...
;             PG8_LDA(At, 1, 1); PG8_STAGE(PG8_SB(1, 0), b3, voffB); PG8_STAGE(PG8_SB(1, 1), b3 + hstep, voffB); PG8_STAGE(PG8_SA(1, 0), a3, voffA);
;             PG8_WAIT_V(8); PG8_WAIT_L(0); PG8_BAR; PG8_MMA(1, 0, At, B0); PG8_MMA(1, 1, At, B1); PG8_BAR; PG8_SCHED;
	s_add_i32 s30, s59, s35
	v_lshl_add_u64 v[180:181], v[180:181], 0, s[12:13]
	s_mov_b32 m0, s30
	ds_read_b128 v[190:193], v154 offset:49152
	ds_read_b128 v[194:197], v154 offset:50176
	ds_read_b128 v[198:201], v154 offset:51200
	ds_read_b128 v[202:205], v154 offset:52224
	ds_read_b128 v[206:209], v154 offset:53248
	ds_read_b128 v[210:213], v154 offset:54272
	ds_read_b128 v[214:217], v154 offset:55296
	ds_read_b128 v[218:221], v154 offset:56320
	global_load_lds_dwordx4 v[180:181], off
	s_add_i32 m0, s30, 0x2000
	s_add_u32 s28, s28, 0x40080
	v_lshl_add_u64 v[180:181], v[222:223], 0, s[12:13]
	s_addc_u32 s29, s29, 0
	s_add_i32 s30, s60, s35
	global_load_lds_dwordx4 v[180:181], off
	v_lshl_add_u64 v[180:181], s[28:29], 0, v[132:133]
	s_mov_b32 m0, s30
	s_nop 0
	global_load_lds_dwordx4 v[180:181], off
	v_lshl_add_u64 v[180:181], s[28:29], 0, v[128:129]
	s_add_i32 m0, s30, 0x2000
	s_nop 0
	global_load_lds_dwordx4 v[180:181], off
	v_lshl_add_u64 v[180:181], v[224:225], 0, s[12:13]
	s_mov_b32 m0, s42
	s_nop 0
	global_load_lds_dwordx4 v[180:181], off
	v_lshl_add_u64 v[180:181], v[226:227], 0, s[12:13]
	s_mov_b32 m0, s43
	s_nop 0
	global_load_lds_dwordx4 v[180:181], off
	s_waitcnt vmcnt(8)
	s_waitcnt lgkmcnt(0)
	s_barrier
	s_setprio 1
	s_waitcnt lgkmcnt(0)
	v_mfma_f32_16x16x32_bf16 v[60:63], v[146:149], v[190:193], v[60:63]
	v_mfma_f32_16x16x32_bf16 v[56:59], v[160:163], v[190:193], v[56:59]
	v_mfma_f32_16x16x32_bf16 v[44:47], v[146:149], v[198:201], v[44:47]
	v_mfma_f32_16x16x32_bf16 v[40:43], v[160:163], v[198:201], v[40:43]
	v_mfma_f32_16x16x32_bf16 v[28:31], v[146:149], v[206:209], v[28:31]
	v_mfma_f32_16x16x32_bf16 v[24:27], v[160:163], v[206:209], v[24:27]
	v_mfma_f32_16x16x32_bf16 v[12:15], v[146:149], v[214:217], v[12:15]
	v_mfma_f32_16x16x32_bf16 v[8:11], v[160:163], v[214:217], v[8:11]
	v_mfma_f32_16x16x32_bf16 v[60:63], v[156:159], v[194:197], v[60:63]
	v_mfma_f32_16x16x32_bf16 v[56:59], v[164:167], v[194:197], v[56:59]
	v_mfma_f32_16x16x32_bf16 v[44:47], v[156:159], v[202:205], v[44:47]
	v_mfma_f32_16x16x32_bf16 v[40:43], v[164:167], v[202:205], v[40:43]
	v_mfma_f32_16x16x32_bf16 v[28:31], v[156:159], v[210:213], v[28:31]
	v_mfma_f32_16x16x32_bf16 v[24:27], v[164:167], v[210:213], v[24:27]
	v_mfma_f32_16x16x32_bf16 v[12:15], v[156:159], v[218:221], v[12:15]
	v_mfma_f32_16x16x32_bf16 v[8:11], v[164:167], v[218:221], v[8:11]
	s_setprio 0
	s_setprio 1
	v_mfma_f32_16x16x32_bf16 v[52:55], v[168:171], v[190:193], v[52:55]
	v_mfma_f32_16x16x32_bf16 v[48:51], v[176:179], v[190:193], v[48:51]
	v_mfma_f32_16x16x32_bf16 v[36:39], v[168:171], v[198:201], v[36:39]
	v_mfma_f32_16x16x32_bf16 v[32:35], v[176:179], v[198:201], v[32:35]
	v_mfma_f32_16x16x32_bf16 v[20:23], v[168:171], v[206:209], v[20:23]
	v_mfma_f32_16x16x32_bf16 v[16:19], v[176:179], v[206:209], v[16:19]
	v_mfma_f32_16x16x32_bf16 v[4:7], v[168:171], v[214:217], v[4:7]
	v_mfma_f32_16x16x32_bf16 v[0:3], v[176:179], v[214:217], v[0:3]
	v_mfma_f32_16x16x32_bf16 v[52:55], v[172:175], v[194:197], v[52:55]
	v_mfma_f32_16x16x32_bf16 v[48:51], v[186:189], v[194:197], v[48:51]
	v_mfma_f32_16x16x32_bf16 v[36:39], v[172:175], v[202:205], v[36:39]
	v_mfma_f32_16x16x32_bf16 v[32:35], v[186:189], v[202:205], v[32:35]
	v_mfma_f32_16x16x32_bf16 v[20:23], v[172:175], v[210:213], v[20:23]
	v_mfma_f32_16x16x32_bf16 v[16:19], v[186:189], v[210:213], v[16:19]
	v_mfma_f32_16x16x32_bf16 v[4:7], v[172:175], v[218:221], v[4:7]
	v_mfma_f32_16x16x32_bf16 v[0:3], v[186:189], v[218:221], v[0:3]
	s_setprio 0
	s_barrier
	s_add_i32 s58, s58, 2
	s_add_u32 s26, s26, 0x100
	s_addc_u32 s27, s27, 0
	s_add_u32 s56, s56, 0x100
	s_addc_u32 s57, s57, 0
	s_cmp_gt_u32 s58, 13

; __device__ __forceinline__ int launder_tid() { int x = threadIdx.x; asm volatile("" : "+v"(x)); return x; }
; #define PG8_STAGE(bufoff, gbase, voff) do { _Pragma("unroll") for (int _i = 0; _i < 2; ++_i) \
;         __builtin_amdgcn_global_load_lds((const unsigned*)((const char*)(gbase) + (voff)[_i]), (PG8_LAS unsigned*)(lds + (bufoff) + ldsw + _i * 8192), 16, 0, 0); } while (0)
; template <class Epi, class Sched, bool ALIGN_EPI = false, bool SP2 = false>
; __device__ __forceinline__ void gemm_phase(PG8_LAS unsigned char* lds, const Gemm g, const Sched& S, const Epi& E) {
;     const int tid = launder_tid(), wid = __builtin_amdgcn_readfirstlane(tid >> 6), lane = tid & 63, wr = wid >> 2, wc = wid & 3, fr = lane & 15, fq = lane >> 4;
;     const int K = g.K, nt = K / BK;
;     unsigned voffA[2], voffB[2];
; #pragma unroll
;     for (int i = 0; i < 2; ++i) { int R, C; stage_rc(tid * 16 + i * 8192, R, C); const int Rb = Epi::PERM ? ((R & ~31) + perm32(R & 31)) : R;
;         voffA[i] = (unsigned)(R * K + C) * 2u; voffB[i] = (unsigned)(Rb * K + C) * 2u; }
;     const size_t kstep = (size_t)(BK * 2);
;     const size_t hstep = (size_t)HALF * K * 2;
;     const size_t tstep = 2 * hstep;
;     const unsigned ldsw = (unsigned)wid * 1024u;
;     const int aoff = lds_byte(wr * 64 + fr, fq * 8), boff = lds_byte(wc * 32 + fr, fq * 8);
;     ...
;     Unit cur, nxt; int ui = 0;
;     if (!S.next(0, cur)) return;
;     f32x4 acc[2][2][4][2];
; #pragma unroll
;     for (int a = 0; a < 2; ++a)
; #pragma unroll
;         for (int b = 0; b < 2; ++b)
; #pragma unroll
;             for (int m = 0; m < 4; ++m)
; #pragma unroll
;                 for (int n = 0; n < 2; ++n) acc[a][b][m][n] = (f32x4){0.f, 0.f, 0.f, 0.f};
;     bf16x8 At[4][2], B0[2][2], B1[2][2];
;     const char* cA = (const char*)g.A + (size_t)cur.pm * tstep; const char* cB = (const char*)g.Bt + (size_t)cur.pn * tstep;
;     S.a_ready(cur);
;     if constexpr (SP2) {
;         PG8_STAGE(PG8_SB(0, 0), cB, voffB); PG8_STAGE(PG8_SB(0, 1), cB + hstep, voffB); PG8_STAGE(PG8_SA(0, 0), cA, voffA); PG8_STAGE(PG8_SA(0, 1), cA + hstep, voffA);
;         if (wr == 1) PG8_BAR;
;         PG8_WAIT_V(2); PG8_BAR;
;         PG8_STAGE(PG8_SB(1, 0), cB + kstep, voffB); PG8_STAGE(PG8_SA(1, 0), cA + kstep, voffA); PG8_STAGE(PG8_SB(1, 1), cB + hstep + kstep, voffB);
;         PG8_WAIT_V(6); PG8_BAR;
.LBB0_885:
	s_or_b64 exec, exec, s[0:1]
	v_mov_b32_e32 v253, v182
	s_movk_i32 s98, 40
	s_movk_i32 s99, 41
	s_barrier
	s_and_b64 vcc, exec, s[4:5]
	v_readfirstlane_b32 s4, v182
	s_cbranch_vccnz .LBB0_905
	v_lshlrev_b32_e32 v12, 4, v182
	v_add_u32_e32 v0, 0x2000, v12
	v_ashrrev_i32_e32 v1, 31, v0
	v_lshrrev_b32_e32 v1, 22, v1
	v_add_u32_e32 v1, v0, v1
	v_ashrrev_i32_e32 v8, 10, v1
	v_mul_i32_i24_e32 v1, 0x400, v8
	v_sub_u32_e32 v0, v0, v1
	v_lshrrev_b32_e32 v1, 4, v0
	v_bitop3_b32 v0, v1, v0, 32 bitop3:0x6c
	v_ashrrev_i32_e32 v1, 31, v0
	v_lshrrev_b32_e32 v1, 26, v1
	v_add_u32_e32 v1, v0, v1
	v_lshlrev_b32_e32 v2, 3, v8
	v_ashrrev_i32_e32 v9, 6, v1
	v_and_b32_e32 v2, -16, v2
	v_add_u32_e32 v2, v9, v2
	v_and_b32_e32 v3, 3, v9
	s_mov_b32 s0, 0xffffe0
	v_lshrrev_b32_e32 v4, 2, v2
	v_lshlrev_b32_e32 v5, 1, v2
	v_and_b32_e32 v1, 0xc0, v1
	v_and_or_b32 v3, v2, s0, v3
	v_and_b32_e32 v4, 4, v4
	v_and_b32_e32 v5, 24, v5
	v_sub_u32_e32 v0, v0, v1
	v_mov_b32_e32 v1, 1
	v_or3_b32 v3, v3, v4, v5
	v_lshlrev_b32_e32 v4, 5, v8
	v_ashrrev_i16_sdwa v0, v1, sext(v0) dst_sel:DWORD dst_unused:UNUSED_PAD src0_sel:DWORD src1_sel:BYTE_0
	s_movk_i32 s1, 0xb00
	v_and_b32_e32 v10, 32, v4
	v_bfe_i32 v11, v0, 0, 16
	v_mul_u32_u24_e32 v3, 0xb00, v3
	v_add_u32_e32 v0, v10, v11
	v_mul_lo_u32 v2, v2, s1
	v_add_lshl_u32 v128, v3, v0, 1
	v_add_lshl_u32 v130, v0, v2, 1
	v_bfe_i32 v0, v182, 27, 1
	v_lshrrev_b32_e32 v0, 22, v0
	v_add_u32_e32 v0, v12, v0
	v_and_b32_e32 v0, 0xfffffc00, v0
	v_sub_u32_e32 v0, v12, v0
	v_lshrrev_b32_e32 v2, 4, v0
	v_bitop3_b32 v2, v2, v0, 32 bitop3:0x6c
	v_ashrrev_i32_e32 v0, 31, v0
	v_lshrrev_b32_e32 v0, 26, v0
	v_add_u32_e32 v0, v2, v0
	v_ashrrev_i32_e32 v13, 6, v0
	v_ashrrev_i32_e32 v0, 31, v182
	v_lshrrev_b32_e32 v0, 26, v0
	v_add_u32_e32 v0, v182, v0
	v_ashrrev_i32_e32 v14, 6, v0
	v_lshlrev_b32_e32 v0, 3, v14
	s_add_u32 s26, s74, 0x1448400
	v_and_b32_e32 v0, -16, v0
	s_addc_u32 s27, s75, 0
	v_add_u32_e32 v0, v13, v0
	v_and_b32_e32 v3, 3, v13
	s_ashr_i32 s29, s2, 31
	v_and_or_b32 v3, v0, s0, v3
	s_lshr_b32 s0, s29, 29
	s_add_i32 s0, s2, s0
	s_ashr_i32 s10, s4, 6
	s_ashr_i32 s6, s0, 3
	s_and_b32 s0, s0, -8
	s_ashr_i32 s5, s4, 8
	s_lshl_b32 s28, s10, 10
	s_sub_i32 s0, s2, s0
	s_cmp_lt_i32 s0, 0
	s_movk_i32 s30, 0x83
	s_cselect_b32 s7, s30, 0x82
	s_mul_i32 s0, s7, s0
	v_lshrrev_b32_e32 v4, 2, v0
	v_lshlrev_b32_e32 v5, 1, v0
	s_add_i32 s0, s0, s6
	v_and_b32_e32 v4, 4, v4
	v_and_b32_e32 v5, 24, v5
	s_ashr_i32 s6, s0, 31
	v_or3_b32 v3, v3, v4, v5
	v_lshlrev_b32_e32 v4, 5, v14
	s_lshr_b32 s6, s6, 27
	v_and_b32_e32 v15, 32, v4
	v_mul_i32_i24_e32 v4, 64, v13
	s_add_i32 s6, s0, s6
	v_sub_u32_e32 v2, v2, v4
	s_ashr_i32 s7, s6, 5
	v_ashrrev_i16_sdwa v1, v1, sext(v2) dst_sel:DWORD dst_unused:UNUSED_PAD src0_sel:DWORD src1_sel:BYTE_0
	s_lshl_b32 s8, s7, 3
	v_bfe_i32 v16, v1, 0, 16
	s_sub_i32 s7, 0x104, s8
	v_mul_u32_u24_e32 v3, 0xb00, v3
	v_add_u32_e32 v1, v15, v16
	s_min_u32 s9, s7, 8
	s_andn2_b32 s6, s6, 31
	v_add_lshl_u32 v132, v3, v1, 1
	s_sub_i32 s11, s0, s6
	v_cvt_f32_ubyte0_e32 v3, s9
	v_cvt_f32_i32_e32 v2, s11
	v_rcp_iflag_f32_e32 v4, v3
	v_mul_lo_u32 v0, v0, s1
	v_add_lshl_u32 v134, v1, v0, 1
	s_ashr_i32 s0, s11, 30
	v_mul_f32_e32 v0, v2, v4
	v_trunc_f32_e32 v0, v0
	v_fma_f32 v1, -v0, v3, v2
	v_cvt_i32_f32_e32 v0, v0
	s_or_b32 s0, s0, 1
	v_cmp_ge_f32_e64 s[6:7], |v1|, v3
	s_and_b64 s[6:7], s[6:7], exec
	s_cselect_b32 s0, s0, 0
	v_readfirstlane_b32 s6, v0
	s_add_i32 s0, s6, s0
	s_mul_i32 s6, s0, s9
	s_sub_i32 s6, s11, s6
	s_sext_i32_i8 s6, s6
	s_add_i32 s6, s8, s6
	s_bfe_i64 s[8:9], s[0:1], 0x80000
	s_mul_hi_i32 s9, s8, 0x160000
	s_mul_i32 s8, s8, 0x160000
	s_add_u32 s18, s26, s8
	s_addc_u32 s19, s27, s9
	s_add_i32 s31, s28, 0
	s_add_i32 m0, s31, 0x10000
	s_mul_i32 s11, s6, 0x160000
	global_load_lds_dwordx4 v132, s[18:19]
	s_add_i32 m0, s31, 0x12000
	s_add_u32 s8, s18, 0xb0000
	global_load_lds_dwordx4 v128, s[18:19]
	s_addc_u32 s9, s19, 0
	s_add_i32 m0, s31, 0x14000
	s_mul_hi_i32 s7, s6, 0x160000
	global_load_lds_dwordx4 v132, s[8:9]
	s_add_i32 m0, s31, 0x16000
	s_add_u32 s16, s52, s11
	s_addc_u32 s17, s53, s7
	s_add_i32 s33, s31, 0x2000
	global_load_lds_dwordx4 v128, s[8:9]
	s_mov_b32 m0, s31
	s_add_u32 s8, s16, 0xb0000
	global_load_lds_dwordx4 v134, s[16:17]
	s_mov_b32 m0, s33
	s_addc_u32 s9, s17, 0
	s_add_i32 s34, s31, 0x4000
	global_load_lds_dwordx4 v130, s[16:17]
	s_mov_b32 m0, s34
	s_add_i32 s35, s31, 0x6000
	global_load_lds_dwordx4 v134, s[8:9]
	s_mov_b32 m0, s35
	v_mov_b32_e32 v137, 0
	global_load_lds_dwordx4 v130, s[8:9]
	v_mov_b32_e32 v133, v137
	v_mov_b32_e32 v129, v137
	v_mov_b32_e32 v135, v137
	v_mov_b32_e32 v131, v137
	s_cmp_eq_u32 s5, 1
	s_mov_b32 s7, 0
	v_lshl_add_u64 v[6:7], s[18:19], 0, v[132:133]
	v_lshl_add_u64 v[4:5], s[18:19], 0, v[128:129]
	v_lshl_add_u64 v[0:1], s[16:17], 0, v[134:135]
	s_cselect_b64 s[8:9], -1, 0
	s_cmp_lg_u32 s5, 1
	v_lshl_add_u64 v[2:3], s[16:17], 0, v[130:131]
	s_cbranch_scc1 .LBB0_888
	s_barrier

;     __host__ __device__ bool next(int i, Unit& u) const {
;         const long L = (long)i * G + c; if (L >= nwg) return false;
;         int wgid = (int)L; { const int q = nwg / NXCD, r = nwg % NXCD, xcd = wgid % NXCD, off = wgid / NXCD; wgid = (xcd < r ? xcd * (q + 1) : r * (q + 1) + (xcd - r) * q) + off; }
;         const int nig = WGM * nN, gid = wgid / nig, fm = gid * WGM, gsz = (nM - fm) < WGM ? (nM - fm) : WGM;
;         u.pm = fm + ((wgid % nig) % gsz); u.pn = (wgid % nig) / gsz; return true;
;     }
; template <class Epi, class Sched, bool ALIGN_EPI = false, bool SP2 = false>
; __device__ __forceinline__ void gemm_phase(PG8_LAS unsigned char* lds, const Gemm g, const Sched& S, const Epi& E) {
;     ...
;         const bool has_next = S.next(ui + 1, nxt);
;         const char* nA = has_next ? (const char*)g.A + (size_t)nxt.pm * tstep : cA; const char* nB = has_next ? (const char*)g.Bt + (size_t)nxt.pn * tstep : cB;
.LBB0_890:
	s_andn2_b64 vcc, exec, s[0:1]
	s_mov_b32 s24, s44
	s_mov_b32 s6, s45
	s_mov_b64 s[18:19], s[14:15]
	s_mov_b64 s[16:17], s[4:5]
	s_mov_b32 s98, s100
	s_mov_b32 s99, s101
	s_cbranch_vccz .LBB0_904
.LBB0_891:
	s_add_i32 s43, s43, 1
	s_mul_i32 s0, s43, s40
	s_mul_hi_u32 s1, s43, s3
	s_add_i32 s1, s1, s0
	s_mul_i32 s0, s43, s3
	s_add_u32 s0, s0, s2
	s_addc_u32 s1, s1, s29
	s_movk_i32 s100, 40
	s_movk_i32 s101, 41
	s_cmp_lg_u32 s43, 4
	s_cbranch_scc1 .Lsk5_norm
	s_cmp_gt_u32 s2, 31
	s_cbranch_scc1 .Lsk5_none
	s_lshr_b32 s0, s2, 1
	s_addk_i32 s0, 0x400
	s_mov_b32 s1, 0
	s_bitcmp1_b32 s2, 0
	s_cselect_b32 s100, 14, 22
	s_cselect_b32 s101, 15, 23
	s_branch .Lsk5_norm
.Lsk5_none:
	s_movk_i32 s0, 0x7fff
	s_mov_b32 s1, 0
.Lsk5_norm:
	v_cmp_gt_i64_e32 vcc, s[0:1], v[156:157]
	v_cmp_lt_i64_e64 s[4:5], s[0:1], v[154:155]
	s_cbranch_vccnz .LBB0_893
	s_ashr_i32 s1, s0, 31
	s_lshr_b32 s1, s1, 29
	s_add_i32 s1, s0, s1
	s_ashr_i32 s14, s1, 3
	s_and_b32 s1, s1, -8
	s_sub_i32 s0, s0, s1
	s_cmp_lt_i32 s0, 0
	s_cselect_b32 s1, s30, 0x82
	s_mul_i32 s0, s1, s0
	s_add_i32 s0, s0, s14
	s_ashr_i32 s1, s0, 31
	s_lshr_b32 s1, s1, 27
	s_add_i32 s1, s0, s1
	s_ashr_i32 s14, s1, 5
	s_lshl_b32 s14, s14, 3
	s_sub_i32 s15, 0x104, s14
	s_min_i32 s15, s15, 8
	s_abs_i32 s20, s15
	v_cvt_f32_u32_e32 v0, s20
	s_sub_i32 s22, 0, s20
	s_andn2_b32 s1, s1, 31
	s_sub_i32 s0, s0, s1
	v_rcp_iflag_f32_e32 v0, v0
	s_abs_i32 s1, s0
	s_xor_b32 s21, s0, s15
	s_ashr_i32 s21, s21, 31
	v_mul_f32_e32 v0, 0x4f7ffffe, v0
	v_cvt_u32_f32_e32 v0, v0
	s_nop 0
	v_readfirstlane_b32 s23, v0
	s_mul_i32 s22, s22, s23
	s_mul_hi_u32 s22, s23, s22
	s_add_i32 s23, s23, s22
	s_mul_hi_u32 s22, s1, s23
	s_mul_i32 s23, s22, s20
	s_sub_i32 s1, s1, s23
	s_add_i32 s25, s22, 1
	s_sub_i32 s23, s1, s20
	s_cmp_ge_u32 s1, s20
	s_cselect_b32 s22, s25, s22
	s_cselect_b32 s1, s23, s1
	s_add_i32 s23, s22, 1
	s_cmp_ge_u32 s1, s20
	s_cselect_b32 s1, s23, s22
	s_xor_b32 s1, s1, s21
	s_sub_i32 s44, s1, s21
	s_mul_i32 s1, s44, s15
	s_sub_i32 s0, s0, s1
	s_add_i32 s45, s0, s14

; #define PG8_STAGE(bufoff, gbase, voff) do { _Pragma("unroll") for (int _i = 0; _i < 2; ++_i) \
;         __builtin_amdgcn_global_load_lds((const unsigned*)((const char*)(gbase) + (voff)[_i]), (PG8_LAS unsigned*)(lds + (bufoff) + ldsw + _i * 8192), 16, 0, 0); } while (0)
; #define PG8_LDA(dst, b, h) do { _Pragma("unroll") for (int m = 0; m < 4; ++m) _Pragma("unroll") for (int k = 0; k < 2; ++k) dst[m][k] = *(const PG8_LAS bf16x8*)(lds + PG8_SA(b, h) + aoff + m * 2048 + k * 1024); } while (0)
; #define PG8_LDB(dst, b, h) do { _Pragma("unroll") for (int n = 0; n < 2; ++n) _Pragma("unroll") for (int k = 0; k < 2; ++k) dst[n][k] = *(const PG8_LAS bf16x8*)(lds + PG8_SB(b, h) + boff + n * 2048 + k * 1024); } while (0)
; #define PG8_MMA(ai, bj, At, Bt) do { __builtin_amdgcn_s_setprio(1); _Pragma("unroll") for (int m = 0; m < 4; ++m) _Pragma("unroll") for (int n = 0; n < 2; ++n) _Pragma("unroll") for (int k = 0; k < 2; ++k) \
;         acc[ai][bj][m][n] = __builtin_amdgcn_mfma_f32_16x16x32_bf16(Bt[n][k], At[m][k], acc[ai][bj][m][n], 0, 0, 0); __builtin_amdgcn_s_setprio(0); } while (0)
; #define PG8_WAIT_V(n) asm volatile("s_waitcnt vmcnt(" #n ")" ::: "memory")
; #define PG8_WAIT_L(n) asm volatile("s_waitcnt lgkmcnt(" #n ")" ::: "memory")
; #define PG8_BAR __builtin_amdgcn_s_barrier()
; #define PG8_SCHED __builtin_amdgcn_sched_barrier(0)
; template <class Epi, class Sched, bool ALIGN_EPI = false, bool SP2 = false>
; __device__ __forceinline__ void gemm_phase(PG8_LAS unsigned char* lds, const Gemm g, const Sched& S, const Epi& E) {
;     ...
;             const char* a1 = cA + (size_t)(t + 1) * kstep;
;             const char* a2 = last ? nA : cA + (size_t)(t + 2) * kstep; const char* b2 = last ? nB : cB + (size_t)(t + 2) * kstep;
;             const char* a3 = a2 + kstep; const char* b3 = b2 + kstep;
;             if (last && has_next) S.a_ready(nxt);
;             if constexpr (SP2) {
;             PG8_LDB(B0, 0, 0); PG8_LDB(B1, 0, 1); PG8_SCHED; PG8_LDA(At, 0, 0); PG8_STAGE(PG8_SA(1, 1), a1 + hstep, voffA);
;             PG8_WAIT_V(8); PG8_WAIT_L(0); PG8_BAR; PG8_MMA(0, 0, At, B0); PG8_MMA(0, 1, At, B1); PG8_BAR; PG8_SCHED;
;             PG8_LDA(At, 0, 1); PG8_STAGE(PG8_SB(0, 0), b2, voffB); PG8_STAGE(PG8_SB(0, 1), b2 + hstep, voffB); PG8_STAGE(PG8_SA(0, 0), a2, voffA);
.LBB0_897:
	s_cmp_eq_u32 s101, 41
	s_cbranch_scc1 .Lsk5_nokoff
	s_and_b32 s76, s2, 1
	s_mulk_i32 s76, 0xd00
	s_add_u32 s4, s4, s76
	s_addc_u32 s5, s5, 0
	s_add_u32 s14, s14, s76
	s_addc_u32 s15, s15, 0
.Lsk5_nokoff:
	s_add_u32 s25, s18, 0x100
	s_addc_u32 s46, s19, 0
	s_mov_b32 s47, -2
	s_waitcnt vmcnt(0)
	ds_read_b128 v[172:175], v169
	ds_read_b128 v[176:179], v169 offset:1024
	ds_read_b128 v[180:183], v169 offset:2048
	ds_read_b128 v[184:187], v169 offset:3072
	ds_read_b128 v[188:191], v170
	ds_read_b128 v[192:195], v170 offset:1024
	ds_read_b128 v[196:199], v170 offset:2048
	ds_read_b128 v[200:203], v170 offset:3072
	s_add_u32 s18, s16, 0x100
	s_addc_u32 s19, s17, 0
	s_cmp_eq_u32 s47, s98
	s_cselect_b32 s23, s5, s19
	s_cselect_b32 s22, s4, s18
	s_cselect_b32 s21, s15, s46
	s_cselect_b32 s20, s14, s25
	v_lshl_add_u64 v[236:237], s[16:17], 0, v[138:139]
	s_add_i32 m0, s31, 0xc000
	ds_read_b128 v[204:207], v160
	ds_read_b128 v[208:211], v160 offset:1024
	ds_read_b128 v[212:215], v160 offset:2048
	ds_read_b128 v[216:219], v160 offset:3072
	ds_read_b128 v[220:223], v160 offset:4096
	ds_read_b128 v[224:227], v160 offset:5120
	ds_read_b128 v[228:231], v160 offset:6144
	ds_read_b128 v[232:235], v160 offset:7168
	global_load_lds_dwordx4 v[236:237], off
	v_lshl_add_u64 v[236:237], s[16:17], 0, v[140:141]
	s_add_i32 m0, s31, 0xe000
	s_nop 0
	global_load_lds_dwordx4 v[236:237], off
	s_waitcnt vmcnt(8)
	s_waitcnt lgkmcnt(0)
	s_barrier
	s_setprio 1
	s_waitcnt lgkmcnt(0)
	v_mfma_f32_16x16x32_bf16 v[124:127], v[172:175], v[204:207], 0
	v_mfma_f32_16x16x32_bf16 v[120:123], v[180:183], v[204:207], 0
	v_mfma_f32_16x16x32_bf16 v[108:111], v[172:175], v[212:215], 0
	v_mfma_f32_16x16x32_bf16 v[104:107], v[180:183], v[212:215], 0
	v_mfma_f32_16x16x32_bf16 v[92:95], v[172:175], v[220:223], 0
	v_mfma_f32_16x16x32_bf16 v[88:91], v[180:183], v[220:223], 0
	v_mfma_f32_16x16x32_bf16 v[76:79], v[172:175], v[228:231], 0
	v_mfma_f32_16x16x32_bf16 v[72:75], v[180:183], v[228:231], 0
	v_mfma_f32_16x16x32_bf16 v[124:127], v[176:179], v[208:211], v[124:127]
	v_mfma_f32_16x16x32_bf16 v[120:123], v[184:187], v[208:211], v[120:123]
	v_mfma_f32_16x16x32_bf16 v[108:111], v[176:179], v[216:219], v[108:111]
	v_mfma_f32_16x16x32_bf16 v[104:107], v[184:187], v[216:219], v[104:107]
	v_mfma_f32_16x16x32_bf16 v[92:95], v[176:179], v[224:227], v[92:95]
	v_mfma_f32_16x16x32_bf16 v[88:91], v[184:187], v[224:227], v[88:91]
	v_mfma_f32_16x16x32_bf16 v[76:79], v[176:179], v[232:235], v[76:79]
	v_mfma_f32_16x16x32_bf16 v[72:75], v[184:187], v[232:235], v[72:75]
	s_setprio 0
	s_setprio 1
	v_mfma_f32_16x16x32_bf16 v[116:119], v[188:191], v[204:207], 0
	v_mfma_f32_16x16x32_bf16 v[112:115], v[196:199], v[204:207], 0
	v_mfma_f32_16x16x32_bf16 v[100:103], v[188:191], v[212:215], 0
	v_mfma_f32_16x16x32_bf16 v[96:99], v[196:199], v[212:215], 0
	v_mfma_f32_16x16x32_bf16 v[84:87], v[188:191], v[220:223], 0
	v_mfma_f32_16x16x32_bf16 v[80:83], v[196:199], v[220:223], 0
	v_mfma_f32_16x16x32_bf16 v[68:71], v[188:191], v[228:231], 0
	v_mfma_f32_16x16x32_bf16 v[64:67], v[196:199], v[228:231], 0
	v_mfma_f32_16x16x32_bf16 v[116:119], v[192:195], v[208:211], v[116:119]
	v_mfma_f32_16x16x32_bf16 v[112:115], v[200:203], v[208:211], v[112:115]
	v_mfma_f32_16x16x32_bf16 v[100:103], v[192:195], v[216:219], v[100:103]
	v_mfma_f32_16x16x32_bf16 v[96:99], v[200:203], v[216:219], v[96:99]
	v_mfma_f32_16x16x32_bf16 v[84:87], v[192:195], v[224:227], v[84:87]
	v_mfma_f32_16x16x32_bf16 v[80:83], v[200:203], v[224:227], v[80:83]
	v_mfma_f32_16x16x32_bf16 v[68:71], v[192:195], v[232:235], v[68:71]
	v_mfma_f32_16x16x32_bf16 v[64:67], v[200:203], v[232:235], v[64:67]
	s_setprio 0
	s_barrier
	s_add_i32 s16, s41, s28
	v_lshl_add_u64 v[236:237], s[20:21], 0, v[132:133]
	s_mov_b32 m0, s16
	ds_read_b128 v[204:207], v160 offset:16384
	ds_read_b128 v[208:211], v160 offset:17408
	ds_read_b128 v[212:215], v160 offset:18432
	ds_read_b128 v[216:219], v160 offset:19456
	ds_read_b128 v[220:223], v160 offset:20480
	ds_read_b128 v[224:227], v160 offset:21504
	ds_read_b128 v[228:231], v160 offset:22528
	ds_read_b128 v[232:235], v160 offset:23552
	global_load_lds_dwordx4 v[236:237], off
	s_add_i32 m0, s16, 0x2000
	s_add_u32 s16, s20, 0xb0000
	v_lshl_add_u64 v[238:239], s[20:21], 0, v[128:129]
	s_addc_u32 s17, s21, 0
	s_add_i32 s48, s42, s28
	global_load_lds_dwordx4 v[238:239], off
	v_lshl_add_u64 v[240:241], s[16:17], 0, v[132:133]
	s_mov_b32 m0, s48
	v_lshl_add_u64 v[242:243], s[22:23], 0, v[130:131]
	global_load_lds_dwordx4 v[240:241], off
	v_lshl_add_u64 v[240:241], s[16:17], 0, v[128:129]
	s_add_i32 m0, s48, 0x2000
	s_nop 0
	global_load_lds_dwordx4 v[240:241], off
	v_lshl_add_u64 v[240:241], s[22:23], 0, v[134:135]
	s_mov_b32 m0, s31
	s_nop 0
	global_load_lds_dwordx4 v[240:241], off
	s_mov_b32 m0, s33
	s_nop 0
	global_load_lds_dwordx4 v[242:243], off
	s_waitcnt vmcnt(8)
	s_waitcnt lgkmcnt(0)
	s_barrier
; #define PG8_STAGE(bufoff, gbase, voff) do { _Pragma("unroll") for (int _i = 0; _i < 2; ++_i) \
;         __builtin_amdgcn_global_load_lds((const unsigned*)((const char*)(gbase) + (voff)[_i]), (PG8_LAS unsigned*)(lds + (bufoff) + ldsw + _i * 8192), 16, 0, 0); } while (0)
; #define PG8_LDA(dst, b, h) do { _Pragma("unroll") for (int m = 0; m < 4; ++m) _Pragma("unroll") for (int k = 0; k < 2; ++k) dst[m][k] = *(const PG8_LAS bf16x8*)(lds + PG8_SA(b, h) + aoff + m * 2048 + k * 1024); } while (0)
; #define PG8_LDB(dst, b, h) do { _Pragma("unroll") for (int n = 0; n < 2; ++n) _Pragma("unroll") for (int k = 0; k < 2; ++k) dst[n][k] = *(const PG8_LAS bf16x8*)(lds + PG8_SB(b, h) + boff + n * 2048 + k * 1024); } while (0)
; #define PG8_MMA(ai, bj, At, Bt) do { __builtin_amdgcn_s_setprio(1); _Pragma("unroll") for (int m = 0; m < 4; ++m) _Pragma("unroll") for (int n = 0; n < 2; ++n) _Pragma("unroll") for (int k = 0; k < 2; ++k) \
;         acc[ai][bj][m][n] = __builtin_amdgcn_mfma_f32_16x16x32_bf16(Bt[n][k], At[m][k], acc[ai][bj][m][n], 0, 0, 0); __builtin_amdgcn_s_setprio(0); } while (0)
; #define PG8_WAIT_V(n) asm volatile("s_waitcnt vmcnt(" #n ")" ::: "memory")
; #define PG8_WAIT_L(n) asm volatile("s_waitcnt lgkmcnt(" #n ")" ::: "memory")
; #define PG8_BAR __builtin_amdgcn_s_barrier()
; #define PG8_SCHED __builtin_amdgcn_sched_barrier(0)
; template <class Epi, class Sched, bool ALIGN_EPI = false, bool SP2 = false>
; __device__ __forceinline__ void gemm_phase(PG8_LAS unsigned char* lds, const Gemm g, const Sched& S, const Epi& E) {
;     ...
;             PG8_WAIT_V(8); PG8_WAIT_L(0); PG8_BAR; PG8_MMA(1, 0, At, B0); PG8_MMA(1, 1, At, B1); PG8_BAR; PG8_SCHED;
;             PG8_LDB(B0, 1, 0); PG8_LDB(B1, 1, 1); PG8_SCHED; PG8_LDA(At, 1, 0); PG8_STAGE(PG8_SA(0, 1), a2 + hstep, voffA);
;             PG8_WAIT_V(8); PG8_WAIT_L(0); PG8_BAR; PG8_MMA(0, 0, At, B0); PG8_MMA(0, 1, At, B1); PG8_BAR; PG8_SCHED;
	s_setprio 1
	s_waitcnt lgkmcnt(0)
	v_mfma_f32_16x16x32_bf16 v[60:63], v[172:175], v[204:207], 0
	v_mfma_f32_16x16x32_bf16 v[56:59], v[180:183], v[204:207], 0
	v_mfma_f32_16x16x32_bf16 v[44:47], v[172:175], v[212:215], 0
	v_mfma_f32_16x16x32_bf16 v[40:43], v[180:183], v[212:215], 0
	v_mfma_f32_16x16x32_bf16 v[28:31], v[172:175], v[220:223], 0
	v_mfma_f32_16x16x32_bf16 v[24:27], v[180:183], v[220:223], 0
	v_mfma_f32_16x16x32_bf16 v[12:15], v[172:175], v[228:231], 0
	v_mfma_f32_16x16x32_bf16 v[8:11], v[180:183], v[228:231], 0
	v_mfma_f32_16x16x32_bf16 v[60:63], v[176:179], v[208:211], v[60:63]
	v_mfma_f32_16x16x32_bf16 v[56:59], v[184:187], v[208:211], v[56:59]
	v_mfma_f32_16x16x32_bf16 v[44:47], v[176:179], v[216:219], v[44:47]
	v_mfma_f32_16x16x32_bf16 v[40:43], v[184:187], v[216:219], v[40:43]
	v_mfma_f32_16x16x32_bf16 v[28:31], v[176:179], v[224:227], v[28:31]
	v_mfma_f32_16x16x32_bf16 v[24:27], v[184:187], v[224:227], v[24:27]
	v_mfma_f32_16x16x32_bf16 v[12:15], v[176:179], v[232:235], v[12:15]
	v_mfma_f32_16x16x32_bf16 v[8:11], v[184:187], v[232:235], v[8:11]
	s_setprio 0
	s_setprio 1
	v_mfma_f32_16x16x32_bf16 v[52:55], v[188:191], v[204:207], 0
	v_mfma_f32_16x16x32_bf16 v[48:51], v[196:199], v[204:207], 0
	v_mfma_f32_16x16x32_bf16 v[36:39], v[188:191], v[212:215], 0
	v_mfma_f32_16x16x32_bf16 v[32:35], v[196:199], v[212:215], 0
	v_mfma_f32_16x16x32_bf16 v[20:23], v[188:191], v[220:223], 0
	v_mfma_f32_16x16x32_bf16 v[16:19], v[196:199], v[220:223], 0
	v_mfma_f32_16x16x32_bf16 v[4:7], v[188:191], v[228:231], 0
	v_mfma_f32_16x16x32_bf16 v[0:3], v[196:199], v[228:231], 0
	v_mfma_f32_16x16x32_bf16 v[52:55], v[192:195], v[208:211], v[52:55]
	v_mfma_f32_16x16x32_bf16 v[48:51], v[200:203], v[208:211], v[48:51]
	v_mfma_f32_16x16x32_bf16 v[36:39], v[192:195], v[216:219], v[36:39]
	v_mfma_f32_16x16x32_bf16 v[32:35], v[200:203], v[216:219], v[32:35]
	v_mfma_f32_16x16x32_bf16 v[20:23], v[192:195], v[224:227], v[20:23]
	v_mfma_f32_16x16x32_bf16 v[16:19], v[200:203], v[224:227], v[16:19]
	v_mfma_f32_16x16x32_bf16 v[4:7], v[192:195], v[232:235], v[4:7]
	v_mfma_f32_16x16x32_bf16 v[0:3], v[200:203], v[232:235], v[0:3]
	s_setprio 0
	s_barrier
	s_add_i32 s48, 0, 0x18000
	v_add_u32_e32 v143, s48, v159
	s_add_i32 s49, 0, 0x1c000
	ds_read_b128 v[172:175], v143
	ds_read_b128 v[176:179], v143 offset:1024
	ds_read_b128 v[180:183], v143 offset:2048
	ds_read_b128 v[184:187], v143 offset:3072
	v_add_u32_e32 v143, s49, v159
	ds_read_b128 v[188:191], v143
	ds_read_b128 v[192:195], v143 offset:1024
	ds_read_b128 v[196:199], v143 offset:2048
	ds_read_b128 v[200:203], v143 offset:3072
	s_add_u32 s16, s22, 0xb0000
	s_addc_u32 s17, s23, 0
	s_mov_b32 m0, s34
	v_lshl_add_u64 v[244:245], s[16:17], 0, v[134:135]
	ds_read_b128 v[204:207], v160 offset:32768
	ds_read_b128 v[208:211], v160 offset:33792
	ds_read_b128 v[212:215], v160 offset:34816
	ds_read_b128 v[216:219], v160 offset:35840
	ds_read_b128 v[220:223], v160 offset:36864
	ds_read_b128 v[224:227], v160 offset:37888
	ds_read_b128 v[228:231], v160 offset:38912
	ds_read_b128 v[232:235], v160 offset:39936
	global_load_lds_dwordx4 v[244:245], off
	v_lshl_add_u64 v[244:245], s[16:17], 0, v[130:131]
	s_mov_b32 m0, s35
	s_nop 0
	global_load_lds_dwordx4 v[244:245], off
	s_waitcnt vmcnt(8)
	s_waitcnt lgkmcnt(0)
	s_barrier
	s_setprio 1
	s_waitcnt lgkmcnt(0)
	v_mfma_f32_16x16x32_bf16 v[124:127], v[172:175], v[204:207], v[124:127]
	v_mfma_f32_16x16x32_bf16 v[120:123], v[180:183], v[204:207], v[120:123]
	v_mfma_f32_16x16x32_bf16 v[108:111], v[172:175], v[212:215], v[108:111]
	v_mfma_f32_16x16x32_bf16 v[104:107], v[180:183], v[212:215], v[104:107]
	v_mfma_f32_16x16x32_bf16 v[92:95], v[172:175], v[220:223], v[92:95]
	v_mfma_f32_16x16x32_bf16 v[88:91], v[180:183], v[220:223], v[88:91]
	v_mfma_f32_16x16x32_bf16 v[76:79], v[172:175], v[228:231], v[76:79]
	v_mfma_f32_16x16x32_bf16 v[72:75], v[180:183], v[228:231], v[72:75]
	v_mfma_f32_16x16x32_bf16 v[124:127], v[176:179], v[208:211], v[124:127]
	v_mfma_f32_16x16x32_bf16 v[120:123], v[184:187], v[208:211], v[120:123]
	v_mfma_f32_16x16x32_bf16 v[108:111], v[176:179], v[216:219], v[108:111]
	v_mfma_f32_16x16x32_bf16 v[104:107], v[184:187], v[216:219], v[104:107]
	v_mfma_f32_16x16x32_bf16 v[92:95], v[176:179], v[224:227], v[92:95]
	v_mfma_f32_16x16x32_bf16 v[88:91], v[184:187], v[224:227], v[88:91]
	v_mfma_f32_16x16x32_bf16 v[76:79], v[176:179], v[232:235], v[76:79]
	v_mfma_f32_16x16x32_bf16 v[72:75], v[184:187], v[232:235], v[72:75]
	s_setprio 0
	s_setprio 1
	v_mfma_f32_16x16x32_bf16 v[116:119], v[188:191], v[204:207], v[116:119]
	v_mfma_f32_16x16x32_bf16 v[112:115], v[196:199], v[204:207], v[112:115]
	v_mfma_f32_16x16x32_bf16 v[100:103], v[188:191], v[212:215], v[100:103]
	v_mfma_f32_16x16x32_bf16 v[96:99], v[196:199], v[212:215], v[96:99]
	v_mfma_f32_16x16x32_bf16 v[84:87], v[188:191], v[220:223], v[84:87]
	v_mfma_f32_16x16x32_bf16 v[80:83], v[196:199], v[220:223], v[80:83]
	v_mfma_f32_16x16x32_bf16 v[68:71], v[188:191], v[228:231], v[68:71]
	v_mfma_f32_16x16x32_bf16 v[64:67], v[196:199], v[228:231], v[64:67]
	v_mfma_f32_16x16x32_bf16 v[116:119], v[192:195], v[208:211], v[116:119]
	v_mfma_f32_16x16x32_bf16 v[112:115], v[200:203], v[208:211], v[112:115]
	v_mfma_f32_16x16x32_bf16 v[100:103], v[192:195], v[216:219], v[100:103]
	v_mfma_f32_16x16x32_bf16 v[96:99], v[200:203], v[216:219], v[96:99]
	v_mfma_f32_16x16x32_bf16 v[84:87], v[192:195], v[224:227], v[84:87]
	v_mfma_f32_16x16x32_bf16 v[80:83], v[200:203], v[224:227], v[80:83]
	v_mfma_f32_16x16x32_bf16 v[68:71], v[192:195], v[232:235], v[68:71]
	v_mfma_f32_16x16x32_bf16 v[64:67], v[200:203], v[232:235], v[64:67]
	s_setprio 0
	s_barrier
; #define PG8_STAGE(bufoff, gbase, voff) do { _Pragma("unroll") for (int _i = 0; _i < 2; ++_i) \
;         __builtin_amdgcn_global_load_lds((const unsigned*)((const char*)(gbase) + (voff)[_i]), (PG8_LAS unsigned*)(lds + (bufoff) + ldsw + _i * 8192), 16, 0, 0); } while (0)
; #define PG8_LDA(dst, b, h) do { _Pragma("unroll") for (int m = 0; m < 4; ++m) _Pragma("unroll") for (int k = 0; k < 2; ++k) dst[m][k] = *(const PG8_LAS bf16x8*)(lds + PG8_SA(b, h) + aoff + m * 2048 + k * 1024); } while (0)
; #define PG8_LDB(dst, b, h) do { _Pragma("unroll") for (int n = 0; n < 2; ++n) _Pragma("unroll") for (int k = 0; k < 2; ++k) dst[n][k] = *(const PG8_LAS bf16x8*)(lds + PG8_SB(b, h) + boff + n * 2048 + k * 1024); } while (0)
; #define PG8_MMA(ai, bj, At, Bt) do { __builtin_amdgcn_s_setprio(1); _Pragma("unroll") for (int m = 0; m < 4; ++m) _Pragma("unroll") for (int n = 0; n < 2; ++n) _Pragma("unroll") for (int k = 0; k < 2; ++k) \
;         acc[ai][bj][m][n] = __builtin_amdgcn_mfma_f32_16x16x32_bf16(Bt[n][k], At[m][k], acc[ai][bj][m][n], 0, 0, 0); __builtin_amdgcn_s_setprio(0); } while (0)
; #define PG8_WAIT_V(n) asm volatile("s_waitcnt vmcnt(" #n ")" ::: "memory")
; template <class Epi, class Sched, bool ALIGN_EPI = false, bool SP2 = false>
; __device__ __forceinline__ void gemm_phase(PG8_LAS unsigned char* lds, const Gemm g, const Sched& S, const Epi& E) {
;     ...
;             PG8_LDB(B0, 0, 0); PG8_LDB(B1, 0, 1); PG8_SCHED; PG8_LDA(At, 0, 0); PG8_STAGE(PG8_SA(1, 1), a1 + hstep, voffA);
;             PG8_WAIT_V(8); PG8_WAIT_L(0); PG8_BAR; PG8_MMA(0, 0, At, B0); PG8_MMA(0, 1, At, B1); PG8_BAR; PG8_SCHED;
;             PG8_LDA(At, 0, 1); PG8_STAGE(PG8_SB(0, 0), b2, voffB); PG8_STAGE(PG8_SB(0, 1), b2 + hstep, voffB); PG8_STAGE(PG8_SA(0, 0), a2, voffA);
;             PG8_WAIT_V(8); PG8_WAIT_L(0); PG8_BAR; PG8_MMA(1, 0, At, B0); PG8_MMA(1, 1, At, B1); PG8_BAR; PG8_SCHED;
;             PG8_LDB(B0, 1, 0); PG8_LDB(B1, 1, 1); PG8_SCHED; PG8_LDA(At, 1, 0); PG8_STAGE(PG8_SA(0, 1), a2 + hstep, voffA);
;             PG8_WAIT_V(8); PG8_WAIT_L(0); PG8_BAR; PG8_MMA(0, 0, At, B0); PG8_MMA(0, 1, At, B1); PG8_BAR; PG8_SCHED;
;             PG8_LDA(At, 1, 1); PG8_STAGE(PG8_SB(1, 0), b3, voffB); PG8_STAGE(PG8_SB(1, 1), b3 + hstep, voffB); PG8_STAGE(PG8_SA(1, 0), a3, voffA);
;             PG8_WAIT_V(8); PG8_WAIT_L(0); PG8_BAR; PG8_MMA(1, 0, At, B0); PG8_MMA(1, 1, At, B1); PG8_BAR; PG8_SCHED;
	s_add_i32 s16, s48, s28
	v_lshl_add_u64 v[236:237], v[236:237], 0, s[10:11]
	s_mov_b32 m0, s16
	ds_read_b128 v[204:207], v160 offset:49152
	ds_read_b128 v[208:211], v160 offset:50176
	ds_read_b128 v[212:215], v160 offset:51200
	ds_read_b128 v[216:219], v160 offset:52224
	ds_read_b128 v[220:223], v160 offset:53248
	ds_read_b128 v[224:227], v160 offset:54272
	ds_read_b128 v[228:231], v160 offset:55296
	ds_read_b128 v[232:235], v160 offset:56320
	global_load_lds_dwordx4 v[236:237], off
	s_add_i32 m0, s16, 0x2000
	s_add_u32 s16, s20, 0xb0080
	v_lshl_add_u64 v[236:237], v[238:239], 0, s[10:11]
	s_addc_u32 s17, s21, 0
	s_add_i32 s20, s49, s28
	global_load_lds_dwordx4 v[236:237], off
	v_lshl_add_u64 v[236:237], s[16:17], 0, v[132:133]
	s_mov_b32 m0, s20
	s_nop 0
	global_load_lds_dwordx4 v[236:237], off
	v_lshl_add_u64 v[236:237], s[16:17], 0, v[128:129]
	s_add_i32 m0, s20, 0x2000
	s_nop 0
	global_load_lds_dwordx4 v[236:237], off
	v_lshl_add_u64 v[236:237], v[240:241], 0, s[10:11]
	s_mov_b32 m0, s38
	s_nop 0
	global_load_lds_dwordx4 v[236:237], off
	v_lshl_add_u64 v[236:237], v[242:243], 0, s[10:11]
	s_mov_b32 m0, s39
	s_nop 0
	global_load_lds_dwordx4 v[236:237], off
	s_waitcnt vmcnt(8)
	s_waitcnt lgkmcnt(0)
	s_barrier
	s_setprio 1
	s_waitcnt lgkmcnt(0)
	v_mfma_f32_16x16x32_bf16 v[60:63], v[172:175], v[204:207], v[60:63]
	v_mfma_f32_16x16x32_bf16 v[56:59], v[180:183], v[204:207], v[56:59]
	v_mfma_f32_16x16x32_bf16 v[44:47], v[172:175], v[212:215], v[44:47]
	v_mfma_f32_16x16x32_bf16 v[40:43], v[180:183], v[212:215], v[40:43]
	v_mfma_f32_16x16x32_bf16 v[28:31], v[172:175], v[220:223], v[28:31]
	v_mfma_f32_16x16x32_bf16 v[24:27], v[180:183], v[220:223], v[24:27]
	v_mfma_f32_16x16x32_bf16 v[12:15], v[172:175], v[228:231], v[12:15]
	v_mfma_f32_16x16x32_bf16 v[8:11], v[180:183], v[228:231], v[8:11]
	v_mfma_f32_16x16x32_bf16 v[60:63], v[176:179], v[208:211], v[60:63]
	v_mfma_f32_16x16x32_bf16 v[56:59], v[184:187], v[208:211], v[56:59]
	v_mfma_f32_16x16x32_bf16 v[44:47], v[176:179], v[216:219], v[44:47]
	v_mfma_f32_16x16x32_bf16 v[40:43], v[184:187], v[216:219], v[40:43]
	v_mfma_f32_16x16x32_bf16 v[28:31], v[176:179], v[224:227], v[28:31]
	v_mfma_f32_16x16x32_bf16 v[24:27], v[184:187], v[224:227], v[24:27]
	v_mfma_f32_16x16x32_bf16 v[12:15], v[176:179], v[232:235], v[12:15]
	v_mfma_f32_16x16x32_bf16 v[8:11], v[184:187], v[232:235], v[8:11]
	s_setprio 0
	s_setprio 1
	v_mfma_f32_16x16x32_bf16 v[52:55], v[188:191], v[204:207], v[52:55]
	v_mfma_f32_16x16x32_bf16 v[48:51], v[196:199], v[204:207], v[48:51]
	v_mfma_f32_16x16x32_bf16 v[36:39], v[188:191], v[212:215], v[36:39]
	v_mfma_f32_16x16x32_bf16 v[32:35], v[196:199], v[212:215], v[32:35]
	v_mfma_f32_16x16x32_bf16 v[20:23], v[188:191], v[220:223], v[20:23]
	v_mfma_f32_16x16x32_bf16 v[16:19], v[196:199], v[220:223], v[16:19]
	v_mfma_f32_16x16x32_bf16 v[4:7], v[188:191], v[228:231], v[4:7]
	v_mfma_f32_16x16x32_bf16 v[0:3], v[196:199], v[228:231], v[0:3]
	v_mfma_f32_16x16x32_bf16 v[52:55], v[192:195], v[208:211], v[52:55]
	v_mfma_f32_16x16x32_bf16 v[48:51], v[200:203], v[208:211], v[48:51]
	v_mfma_f32_16x16x32_bf16 v[36:39], v[192:195], v[216:219], v[36:39]
	v_mfma_f32_16x16x32_bf16 v[32:35], v[200:203], v[216:219], v[32:35]
	v_mfma_f32_16x16x32_bf16 v[20:23], v[192:195], v[224:227], v[20:23]
	v_mfma_f32_16x16x32_bf16 v[16:19], v[200:203], v[224:227], v[16:19]
	v_mfma_f32_16x16x32_bf16 v[4:7], v[192:195], v[232:235], v[4:7]
	v_mfma_f32_16x16x32_bf16 v[0:3], v[200:203], v[232:235], v[0:3]
	s_setprio 0
	s_barrier
	s_add_i32 s47, s47, 2
	s_add_u32 s25, s25, 0x100
	s_addc_u32 s46, s46, 0
	s_cmp_gt_u32 s47, s99
	s_mov_b64 s[16:17], s[18:19]
.LBB0_898:
	ds_read_b128 v[172:175], v169
	ds_read_b128 v[176:179], v169 offset:1024
	ds_read_b128 v[180:183], v169 offset:2048
	ds_read_b128 v[184:187], v169 offset:3072
	ds_read_b128 v[188:191], v170
	ds_read_b128 v[192:195], v170 offset:1024
	ds_read_b128 v[196:199], v170 offset:2048
	ds_read_b128 v[200:203], v170 offset:3072
	s_add_u32 s18, s16, 0x100
	s_addc_u32 s19, s17, 0
	s_cmp_eq_u32 s47, s98
	s_cselect_b32 s23, s5, s19
	s_cselect_b32 s22, s4, s18
	s_cselect_b32 s21, s15, s46
	s_cselect_b32 s20, s14, s25
	v_lshl_add_u64 v[236:237], s[16:17], 0, v[138:139]
	s_add_i32 m0, s31, 0xc000
	ds_read_b128 v[204:207], v160
	ds_read_b128 v[208:211], v160 offset:1024
	ds_read_b128 v[212:215], v160 offset:2048
	ds_read_b128 v[216:219], v160 offset:3072
	ds_read_b128 v[220:223], v160 offset:4096
	ds_read_b128 v[224:227], v160 offset:5120
	ds_read_b128 v[228:231], v160 offset:6144
	ds_read_b128 v[232:235], v160 offset:7168
	global_load_lds_dwordx4 v[236:237], off
	v_lshl_add_u64 v[236:237], s[16:17], 0, v[140:141]
	s_add_i32 m0, s31, 0xe000
	s_nop 0
	global_load_lds_dwordx4 v[236:237], off
	s_waitcnt vmcnt(8)
	s_waitcnt lgkmcnt(0)
	s_barrier
; #define PG8_STAGE(bufoff, gbase, voff) do { _Pragma("unroll") for (int _i = 0; _i < 2; ++_i) \
;         __builtin_amdgcn_global_load_lds((const unsigned*)((const char*)(gbase) + (voff)[_i]), (PG8_LAS unsigned*)(lds + (bufoff) + ldsw + _i * 8192), 16, 0, 0); } while (0)
; #define PG8_LDA(dst, b, h) do { _Pragma("unroll") for (int m = 0; m < 4; ++m) _Pragma("unroll") for (int k = 0; k < 2; ++k) dst[m][k] = *(const PG8_LAS bf16x8*)(lds + PG8_SA(b, h) + aoff + m * 2048 + k * 1024); } while (0)
; #define PG8_MMA(ai, bj, At, Bt) do { __builtin_amdgcn_s_setprio(1); _Pragma("unroll") for (int m = 0; m < 4; ++m) _Pragma("unroll") for (int n = 0; n < 2; ++n) _Pragma("unroll") for (int k = 0; k < 2; ++k) \
;         acc[ai][bj][m][n] = __builtin_amdgcn_mfma_f32_16x16x32_bf16(Bt[n][k], At[m][k], acc[ai][bj][m][n], 0, 0, 0); __builtin_amdgcn_s_setprio(0); } while (0)
; #define PG8_WAIT_V(n) asm volatile("s_waitcnt vmcnt(" #n ")" ::: "memory")
; #define PG8_WAIT_L(n) asm volatile("s_waitcnt lgkmcnt(" #n ")" ::: "memory")
; #define PG8_BAR __builtin_amdgcn_s_barrier()
; #define PG8_SCHED __builtin_amdgcn_sched_barrier(0)
; template <class Epi, class Sched, bool ALIGN_EPI = false, bool SP2 = false>
; __device__ __forceinline__ void gemm_phase(PG8_LAS unsigned char* lds, const Gemm g, const Sched& S, const Epi& E) {
;     ...
;             PG8_WAIT_V(8); PG8_WAIT_L(0); PG8_BAR; PG8_MMA(0, 0, At, B0); PG8_MMA(0, 1, At, B1); PG8_BAR; PG8_SCHED;
;             PG8_LDA(At, 0, 1); PG8_STAGE(PG8_SB(0, 0), b2, voffB); PG8_STAGE(PG8_SB(0, 1), b2 + hstep, voffB); PG8_STAGE(PG8_SA(0, 0), a2, voffA);
;             PG8_WAIT_V(8); PG8_WAIT_L(0); PG8_BAR; PG8_MMA(1, 0, At, B0); PG8_MMA(1, 1, At, B1); PG8_BAR; PG8_SCHED;
	s_setprio 1
	s_waitcnt lgkmcnt(0)
	v_mfma_f32_16x16x32_bf16 v[124:127], v[172:175], v[204:207], v[124:127]
	v_mfma_f32_16x16x32_bf16 v[120:123], v[180:183], v[204:207], v[120:123]
	v_mfma_f32_16x16x32_bf16 v[108:111], v[172:175], v[212:215], v[108:111]
	v_mfma_f32_16x16x32_bf16 v[104:107], v[180:183], v[212:215], v[104:107]
	v_mfma_f32_16x16x32_bf16 v[92:95], v[172:175], v[220:223], v[92:95]
	v_mfma_f32_16x16x32_bf16 v[88:91], v[180:183], v[220:223], v[88:91]
	v_mfma_f32_16x16x32_bf16 v[76:79], v[172:175], v[228:231], v[76:79]
	v_mfma_f32_16x16x32_bf16 v[72:75], v[180:183], v[228:231], v[72:75]
	v_mfma_f32_16x16x32_bf16 v[124:127], v[176:179], v[208:211], v[124:127]
	v_mfma_f32_16x16x32_bf16 v[120:123], v[184:187], v[208:211], v[120:123]
	v_mfma_f32_16x16x32_bf16 v[108:111], v[176:179], v[216:219], v[108:111]
	v_mfma_f32_16x16x32_bf16 v[104:107], v[184:187], v[216:219], v[104:107]
	v_mfma_f32_16x16x32_bf16 v[92:95], v[176:179], v[224:227], v[92:95]
	v_mfma_f32_16x16x32_bf16 v[88:91], v[184:187], v[224:227], v[88:91]
	v_mfma_f32_16x16x32_bf16 v[76:79], v[176:179], v[232:235], v[76:79]
	v_mfma_f32_16x16x32_bf16 v[72:75], v[184:187], v[232:235], v[72:75]
	s_setprio 0
	s_setprio 1
	v_mfma_f32_16x16x32_bf16 v[116:119], v[188:191], v[204:207], v[116:119]
	v_mfma_f32_16x16x32_bf16 v[112:115], v[196:199], v[204:207], v[112:115]
	v_mfma_f32_16x16x32_bf16 v[100:103], v[188:191], v[212:215], v[100:103]
	v_mfma_f32_16x16x32_bf16 v[96:99], v[196:199], v[212:215], v[96:99]
	v_mfma_f32_16x16x32_bf16 v[84:87], v[188:191], v[220:223], v[84:87]
	v_mfma_f32_16x16x32_bf16 v[80:83], v[196:199], v[220:223], v[80:83]
	v_mfma_f32_16x16x32_bf16 v[68:71], v[188:191], v[228:231], v[68:71]
	v_mfma_f32_16x16x32_bf16 v[64:67], v[196:199], v[228:231], v[64:67]
	v_mfma_f32_16x16x32_bf16 v[116:119], v[192:195], v[208:211], v[116:119]
	v_mfma_f32_16x16x32_bf16 v[112:115], v[200:203], v[208:211], v[112:115]
	v_mfma_f32_16x16x32_bf16 v[100:103], v[192:195], v[216:219], v[100:103]
	v_mfma_f32_16x16x32_bf16 v[96:99], v[200:203], v[216:219], v[96:99]
	v_mfma_f32_16x16x32_bf16 v[84:87], v[192:195], v[224:227], v[84:87]
	v_mfma_f32_16x16x32_bf16 v[80:83], v[200:203], v[224:227], v[80:83]
	v_mfma_f32_16x16x32_bf16 v[68:71], v[192:195], v[232:235], v[68:71]
	v_mfma_f32_16x16x32_bf16 v[64:67], v[200:203], v[232:235], v[64:67]
	s_setprio 0
	s_barrier
	s_add_i32 s16, s41, s28
	v_lshl_add_u64 v[236:237], s[20:21], 0, v[132:133]
	s_mov_b32 m0, s16
	ds_read_b128 v[204:207], v160 offset:16384
	ds_read_b128 v[208:211], v160 offset:17408
	ds_read_b128 v[212:215], v160 offset:18432
	ds_read_b128 v[216:219], v160 offset:19456
	ds_read_b128 v[220:223], v160 offset:20480
	ds_read_b128 v[224:227], v160 offset:21504
	ds_read_b128 v[228:231], v160 offset:22528
	ds_read_b128 v[232:235], v160 offset:23552
	global_load_lds_dwordx4 v[236:237], off
	s_add_i32 m0, s16, 0x2000
	s_add_u32 s16, s20, 0xb0000
	v_lshl_add_u64 v[238:239], s[20:21], 0, v[128:129]
	s_addc_u32 s17, s21, 0
	s_add_i32 s48, s42, s28
	global_load_lds_dwordx4 v[238:239], off
	v_lshl_add_u64 v[240:241], s[16:17], 0, v[132:133]
	s_mov_b32 m0, s48
	v_lshl_add_u64 v[242:243], s[22:23], 0, v[130:131]
	global_load_lds_dwordx4 v[240:241], off
	v_lshl_add_u64 v[240:241], s[16:17], 0, v[128:129]
	s_add_i32 m0, s48, 0x2000
	s_nop 0
	global_load_lds_dwordx4 v[240:241], off
	v_lshl_add_u64 v[240:241], s[22:23], 0, v[134:135]
	s_mov_b32 m0, s31
	s_nop 0
	global_load_lds_dwordx4 v[240:241], off
	s_mov_b32 m0, s33
	s_nop 0
	global_load_lds_dwordx4 v[242:243], off
	s_waitcnt vmcnt(8)
	s_waitcnt lgkmcnt(0)
	s_barrier
	s_setprio 1
	s_waitcnt lgkmcnt(0)
	v_mfma_f32_16x16x32_bf16 v[60:63], v[172:175], v[204:207], v[60:63]
	v_mfma_f32_16x16x32_bf16 v[56:59], v[180:183], v[204:207], v[56:59]
	v_mfma_f32_16x16x32_bf16 v[44:47], v[172:175], v[212:215], v[44:47]
	v_mfma_f32_16x16x32_bf16 v[40:43], v[180:183], v[212:215], v[40:43]
	v_mfma_f32_16x16x32_bf16 v[28:31], v[172:175], v[220:223], v[28:31]
	v_mfma_f32_16x16x32_bf16 v[24:27], v[180:183], v[220:223], v[24:27]
	v_mfma_f32_16x16x32_bf16 v[12:15], v[172:175], v[228:231], v[12:15]
	v_mfma_f32_16x16x32_bf16 v[8:11], v[180:183], v[228:231], v[8:11]
	v_mfma_f32_16x16x32_bf16 v[60:63], v[176:179], v[208:211], v[60:63]
	v_mfma_f32_16x16x32_bf16 v[56:59], v[184:187], v[208:211], v[56:59]
	v_mfma_f32_16x16x32_bf16 v[44:47], v[176:179], v[216:219], v[44:47]
	v_mfma_f32_16x16x32_bf16 v[40:43], v[184:187], v[216:219], v[40:43]
	v_mfma_f32_16x16x32_bf16 v[28:31], v[176:179], v[224:227], v[28:31]
	v_mfma_f32_16x16x32_bf16 v[24:27], v[184:187], v[224:227], v[24:27]
	v_mfma_f32_16x16x32_bf16 v[12:15], v[176:179], v[232:235], v[12:15]
	v_mfma_f32_16x16x32_bf16 v[8:11], v[184:187], v[232:235], v[8:11]
	s_setprio 0
	s_setprio 1
	v_mfma_f32_16x16x32_bf16 v[52:55], v[188:191], v[204:207], v[52:55]
	v_mfma_f32_16x16x32_bf16 v[48:51], v[196:199], v[204:207], v[48:51]
	v_mfma_f32_16x16x32_bf16 v[36:39], v[188:191], v[212:215], v[36:39]
	v_mfma_f32_16x16x32_bf16 v[32:35], v[196:199], v[212:215], v[32:35]
	v_mfma_f32_16x16x32_bf16 v[20:23], v[188:191], v[220:223], v[20:23]
	v_mfma_f32_16x16x32_bf16 v[16:19], v[196:199], v[220:223], v[16:19]
	v_mfma_f32_16x16x32_bf16 v[4:7], v[188:191], v[228:231], v[4:7]
	v_mfma_f32_16x16x32_bf16 v[0:3], v[196:199], v[228:231], v[0:3]
	v_mfma_f32_16x16x32_bf16 v[52:55], v[192:195], v[208:211], v[52:55]
	v_mfma_f32_16x16x32_bf16 v[48:51], v[200:203], v[208:211], v[48:51]
	v_mfma_f32_16x16x32_bf16 v[36:39], v[192:195], v[216:219], v[36:39]
	v_mfma_f32_16x16x32_bf16 v[32:35], v[200:203], v[216:219], v[32:35]
	v_mfma_f32_16x16x32_bf16 v[20:23], v[192:195], v[224:227], v[20:23]
	v_mfma_f32_16x16x32_bf16 v[16:19], v[200:203], v[224:227], v[16:19]
	v_mfma_f32_16x16x32_bf16 v[4:7], v[192:195], v[232:235], v[4:7]
	v_mfma_f32_16x16x32_bf16 v[0:3], v[200:203], v[232:235], v[0:3]
	s_setprio 0
	s_barrier
; #define PG8_STAGE(bufoff, gbase, voff) do { _Pragma("unroll") for (int _i = 0; _i < 2; ++_i) \
;         __builtin_amdgcn_global_load_lds((const unsigned*)((const char*)(gbase) + (voff)[_i]), (PG8_LAS unsigned*)(lds + (bufoff) + ldsw + _i * 8192), 16, 0, 0); } while (0)
; #define PG8_LDA(dst, b, h) do { _Pragma("unroll") for (int m = 0; m < 4; ++m) _Pragma("unroll") for (int k = 0; k < 2; ++k) dst[m][k] = *(const PG8_LAS bf16x8*)(lds + PG8_SA(b, h) + aoff + m * 2048 + k * 1024); } while (0)
; #define PG8_LDB(dst, b, h) do { _Pragma("unroll") for (int n = 0; n < 2; ++n) _Pragma("unroll") for (int k = 0; k < 2; ++k) dst[n][k] = *(const PG8_LAS bf16x8*)(lds + PG8_SB(b, h) + boff + n * 2048 + k * 1024); } while (0)
; #define PG8_MMA(ai, bj, At, Bt) do { __builtin_amdgcn_s_setprio(1); _Pragma("unroll") for (int m = 0; m < 4; ++m) _Pragma("unroll") for (int n = 0; n < 2; ++n) _Pragma("unroll") for (int k = 0; k < 2; ++k) \
;         acc[ai][bj][m][n] = __builtin_amdgcn_mfma_f32_16x16x32_bf16(Bt[n][k], At[m][k], acc[ai][bj][m][n], 0, 0, 0); __builtin_amdgcn_s_setprio(0); } while (0)
; #define PG8_WAIT_V(n) asm volatile("s_waitcnt vmcnt(" #n ")" ::: "memory")
; #define PG8_WAIT_L(n) asm volatile("s_waitcnt lgkmcnt(" #n ")" ::: "memory")
; #define PG8_BAR __builtin_amdgcn_s_barrier()
; #define PG8_SCHED __builtin_amdgcn_sched_barrier(0)
; template <class Epi, class Sched, bool ALIGN_EPI = false, bool SP2 = false>
; __device__ __forceinline__ void gemm_phase(PG8_LAS unsigned char* lds, const Gemm g, const Sched& S, const Epi& E) {
;     ...
;             PG8_LDB(B0, 1, 0); PG8_LDB(B1, 1, 1); PG8_SCHED; PG8_LDA(At, 1, 0); PG8_STAGE(PG8_SA(0, 1), a2 + hstep, voffA);
;             PG8_WAIT_V(8); PG8_WAIT_L(0); PG8_BAR; PG8_MMA(0, 0, At, B0); PG8_MMA(0, 1, At, B1); PG8_BAR; PG8_SCHED;
;             PG8_LDA(At, 1, 1); PG8_STAGE(PG8_SB(1, 0), b3, voffB); PG8_STAGE(PG8_SB(1, 1), b3 + hstep, voffB); PG8_STAGE(PG8_SA(1, 0), a3, voffA);
;             PG8_WAIT_V(8); PG8_WAIT_L(0); PG8_BAR; PG8_MMA(1, 0, At, B0); PG8_MMA(1, 1, At, B1); PG8_BAR; PG8_SCHED;
	s_add_i32 s48, 0, 0x18000
	v_add_u32_e32 v143, s48, v159
	s_add_i32 s49, 0, 0x1c000
	ds_read_b128 v[172:175], v143
	ds_read_b128 v[176:179], v143 offset:1024
	ds_read_b128 v[180:183], v143 offset:2048
	ds_read_b128 v[184:187], v143 offset:3072
	v_add_u32_e32 v143, s49, v159
	ds_read_b128 v[188:191], v143
	ds_read_b128 v[192:195], v143 offset:1024
	ds_read_b128 v[196:199], v143 offset:2048
	ds_read_b128 v[200:203], v143 offset:3072
	s_add_u32 s16, s22, 0xb0000
	s_addc_u32 s17, s23, 0
	s_mov_b32 m0, s34
	v_lshl_add_u64 v[244:245], s[16:17], 0, v[134:135]
	ds_read_b128 v[204:207], v160 offset:32768
	ds_read_b128 v[208:211], v160 offset:33792
	ds_read_b128 v[212:215], v160 offset:34816
	ds_read_b128 v[216:219], v160 offset:35840
	ds_read_b128 v[220:223], v160 offset:36864
	ds_read_b128 v[224:227], v160 offset:37888
	ds_read_b128 v[228:231], v160 offset:38912
	ds_read_b128 v[232:235], v160 offset:39936
	global_load_lds_dwordx4 v[244:245], off
	v_lshl_add_u64 v[244:245], s[16:17], 0, v[130:131]
	s_mov_b32 m0, s35
	s_nop 0
	global_load_lds_dwordx4 v[244:245], off
	s_waitcnt vmcnt(8)
	s_waitcnt lgkmcnt(0)
	s_barrier
	s_setprio 1
	s_waitcnt lgkmcnt(0)
	v_mfma_f32_16x16x32_bf16 v[124:127], v[172:175], v[204:207], v[124:127]
	v_mfma_f32_16x16x32_bf16 v[120:123], v[180:183], v[204:207], v[120:123]
	v_mfma_f32_16x16x32_bf16 v[108:111], v[172:175], v[212:215], v[108:111]
	v_mfma_f32_16x16x32_bf16 v[104:107], v[180:183], v[212:215], v[104:107]
	v_mfma_f32_16x16x32_bf16 v[92:95], v[172:175], v[220:223], v[92:95]
	v_mfma_f32_16x16x32_bf16 v[88:91], v[180:183], v[220:223], v[88:91]
	v_mfma_f32_16x16x32_bf16 v[76:79], v[172:175], v[228:231], v[76:79]
	v_mfma_f32_16x16x32_bf16 v[72:75], v[180:183], v[228:231], v[72:75]
	v_mfma_f32_16x16x32_bf16 v[124:127], v[176:179], v[208:211], v[124:127]
	v_mfma_f32_16x16x32_bf16 v[120:123], v[184:187], v[208:211], v[120:123]
	v_mfma_f32_16x16x32_bf16 v[108:111], v[176:179], v[216:219], v[108:111]
	v_mfma_f32_16x16x32_bf16 v[104:107], v[184:187], v[216:219], v[104:107]
	v_mfma_f32_16x16x32_bf16 v[92:95], v[176:179], v[224:227], v[92:95]
	v_mfma_f32_16x16x32_bf16 v[88:91], v[184:187], v[224:227], v[88:91]
	v_mfma_f32_16x16x32_bf16 v[76:79], v[176:179], v[232:235], v[76:79]
	v_mfma_f32_16x16x32_bf16 v[72:75], v[184:187], v[232:235], v[72:75]
	s_setprio 0
	s_setprio 1
	v_mfma_f32_16x16x32_bf16 v[116:119], v[188:191], v[204:207], v[116:119]
	v_mfma_f32_16x16x32_bf16 v[112:115], v[196:199], v[204:207], v[112:115]
	v_mfma_f32_16x16x32_bf16 v[100:103], v[188:191], v[212:215], v[100:103]
	v_mfma_f32_16x16x32_bf16 v[96:99], v[196:199], v[212:215], v[96:99]
	v_mfma_f32_16x16x32_bf16 v[84:87], v[188:191], v[220:223], v[84:87]
	v_mfma_f32_16x16x32_bf16 v[80:83], v[196:199], v[220:223], v[80:83]
	v_mfma_f32_16x16x32_bf16 v[68:71], v[188:191], v[228:231], v[68:71]
	v_mfma_f32_16x16x32_bf16 v[64:67], v[196:199], v[228:231], v[64:67]
	v_mfma_f32_16x16x32_bf16 v[116:119], v[192:195], v[208:211], v[116:119]
	v_mfma_f32_16x16x32_bf16 v[112:115], v[200:203], v[208:211], v[112:115]
	v_mfma_f32_16x16x32_bf16 v[100:103], v[192:195], v[216:219], v[100:103]
	v_mfma_f32_16x16x32_bf16 v[96:99], v[200:203], v[216:219], v[96:99]
	v_mfma_f32_16x16x32_bf16 v[84:87], v[192:195], v[224:227], v[84:87]
	v_mfma_f32_16x16x32_bf16 v[80:83], v[200:203], v[224:227], v[80:83]
	v_mfma_f32_16x16x32_bf16 v[68:71], v[192:195], v[232:235], v[68:71]
	v_mfma_f32_16x16x32_bf16 v[64:67], v[200:203], v[232:235], v[64:67]
	s_setprio 0
	s_barrier
	s_add_i32 s16, s48, s28
	v_lshl_add_u64 v[236:237], v[236:237], 0, s[10:11]
	s_mov_b32 m0, s16
	ds_read_b128 v[204:207], v160 offset:49152
	ds_read_b128 v[208:211], v160 offset:50176
	ds_read_b128 v[212:215], v160 offset:51200
	ds_read_b128 v[216:219], v160 offset:52224
	ds_read_b128 v[220:223], v160 offset:53248
	ds_read_b128 v[224:227], v160 offset:54272
	ds_read_b128 v[228:231], v160 offset:55296
	ds_read_b128 v[232:235], v160 offset:56320
	global_load_lds_dwordx4 v[236:237], off
	s_add_i32 m0, s16, 0x2000
	s_add_u32 s16, s20, 0xb0080
	v_lshl_add_u64 v[236:237], v[238:239], 0, s[10:11]
	s_addc_u32 s17, s21, 0
	s_add_i32 s20, s49, s28
	global_load_lds_dwordx4 v[236:237], off
	v_lshl_add_u64 v[236:237], s[16:17], 0, v[132:133]
	s_mov_b32 m0, s20
	s_nop 0
	global_load_lds_dwordx4 v[236:237], off
	v_lshl_add_u64 v[236:237], s[16:17], 0, v[128:129]
	s_add_i32 m0, s20, 0x2000
	s_nop 0
	global_load_lds_dwordx4 v[236:237], off
	v_lshl_add_u64 v[236:237], v[240:241], 0, s[10:11]
	s_mov_b32 m0, s38
	s_nop 0
	global_load_lds_dwordx4 v[236:237], off
	v_lshl_add_u64 v[236:237], v[242:243], 0, s[10:11]
	s_mov_b32 m0, s39
	s_nop 0
	global_load_lds_dwordx4 v[236:237], off
	s_waitcnt vmcnt(8)
	s_waitcnt lgkmcnt(0)
	s_barrier
; #define PG8_STAGE(bufoff, gbase, voff) do { _Pragma("unroll") for (int _i = 0; _i < 2; ++_i) \
;         __builtin_amdgcn_global_load_lds((const unsigned*)((const char*)(gbase) + (voff)[_i]), (PG8_LAS unsigned*)(lds + (bufoff) + ldsw + _i * 8192), 16, 0, 0); } while (0)
; #define PG8_LDA(dst, b, h) do { _Pragma("unroll") for (int m = 0; m < 4; ++m) _Pragma("unroll") for (int k = 0; k < 2; ++k) dst[m][k] = *(const PG8_LAS bf16x8*)(lds + PG8_SA(b, h) + aoff + m * 2048 + k * 1024); } while (0)
; #define PG8_WAIT_V(n) asm volatile("s_waitcnt vmcnt(" #n ")" ::: "memory")
; #define PG8_BAR __builtin_amdgcn_s_barrier()
; template <class Epi, class Sched, bool ALIGN_EPI = false, bool SP2 = false>
; __device__ __forceinline__ void gemm_phase(PG8_LAS unsigned char* lds, const Gemm g, const Sched& S, const Epi& E) {
;     ...
;             PG8_WAIT_V(8); PG8_WAIT_L(0); PG8_BAR; PG8_MMA(1, 0, At, B0); PG8_MMA(1, 1, At, B1); PG8_BAR; PG8_SCHED;
;             } else {
;             PG8_LDB(B0, 0, 0); PG8_SCHED; PG8_LDA(At, 0, 0); PG8_STAGE(PG8_SA(1, 1), a1 + hstep, voffA);
;             PG8_WAIT_L(8); PG8_BAR; PG8_WAIT_L(0); PG8_MMA(0, 0, At, B0); PG8_BAR; PG8_SCHED;
;             PG8_LDB(B1, 0, 1); PG8_STAGE(PG8_SB(0, 0), b2, voffB);
;             PG8_BAR; PG8_WAIT_L(0); PG8_MMA(0, 1, At, B1); PG8_BAR;
;             PG8_LDA(At, 0, 1); PG8_STAGE(PG8_SA(0, 0), a2, voffA);
;             PG8_BAR; PG8_WAIT_L(0); PG8_MMA(1, 0, At, B0); PG8_BAR; PG8_SCHED;
;             PG8_STAGE(PG8_SB(0, 1), b2 + hstep, voffB);
;             PG8_WAIT_V(6); PG8_BAR; PG8_MMA(1, 1, At, B1); PG8_BAR;
;             PG8_LDB(B0, 1, 0); PG8_SCHED; PG8_LDA(At, 1, 0); PG8_STAGE(PG8_SA(0, 1), a2 + hstep, voffA);
;             PG8_WAIT_L(8); PG8_BAR; PG8_WAIT_L(0); PG8_MMA(0, 0, At, B0); PG8_BAR; PG8_SCHED;
;             PG8_LDB(B1, 1, 1); PG8_STAGE(PG8_SB(1, 0), b3, voffB);
;             PG8_BAR; PG8_WAIT_L(0); PG8_MMA(0, 1, At, B1); PG8_BAR;
;             PG8_LDA(At, 1, 1); PG8_STAGE(PG8_SA(1, 0), a3, voffA);
;             PG8_BAR; PG8_WAIT_L(0); PG8_MMA(1, 0, At, B0); PG8_BAR; PG8_SCHED;
;             PG8_STAGE(PG8_SB(1, 1), b3 + hstep, voffB);
;             PG8_WAIT_V(6); PG8_BAR; PG8_MMA(1, 1, At, B1); PG8_BAR;
;             }
;         }
;         if constexpr (ALIGN_EPI) { if (wr == 0) PG8_BAR; }
;         if constexpr (!Epi::AFTER_DRAIN) { E(acc, cur, wr, wc, fr, fq); S.done(cur); }
	s_setprio 1
	s_waitcnt lgkmcnt(0)
	v_mfma_f32_16x16x32_bf16 v[60:63], v[172:175], v[204:207], v[60:63]
	v_mfma_f32_16x16x32_bf16 v[56:59], v[180:183], v[204:207], v[56:59]
	v_mfma_f32_16x16x32_bf16 v[44:47], v[172:175], v[212:215], v[44:47]
	v_mfma_f32_16x16x32_bf16 v[40:43], v[180:183], v[212:215], v[40:43]
	v_mfma_f32_16x16x32_bf16 v[28:31], v[172:175], v[220:223], v[28:31]
	v_mfma_f32_16x16x32_bf16 v[24:27], v[180:183], v[220:223], v[24:27]
	v_mfma_f32_16x16x32_bf16 v[12:15], v[172:175], v[228:231], v[12:15]
	v_mfma_f32_16x16x32_bf16 v[8:11], v[180:183], v[228:231], v[8:11]
	v_mfma_f32_16x16x32_bf16 v[60:63], v[176:179], v[208:211], v[60:63]
	v_mfma_f32_16x16x32_bf16 v[56:59], v[184:187], v[208:211], v[56:59]
	v_mfma_f32_16x16x32_bf16 v[44:47], v[176:179], v[216:219], v[44:47]
	v_mfma_f32_16x16x32_bf16 v[40:43], v[184:187], v[216:219], v[40:43]
	v_mfma_f32_16x16x32_bf16 v[28:31], v[176:179], v[224:227], v[28:31]
	v_mfma_f32_16x16x32_bf16 v[24:27], v[184:187], v[224:227], v[24:27]
	v_mfma_f32_16x16x32_bf16 v[12:15], v[176:179], v[232:235], v[12:15]
	v_mfma_f32_16x16x32_bf16 v[8:11], v[184:187], v[232:235], v[8:11]
	s_setprio 0
	s_setprio 1
	v_mfma_f32_16x16x32_bf16 v[52:55], v[188:191], v[204:207], v[52:55]
	v_mfma_f32_16x16x32_bf16 v[48:51], v[196:199], v[204:207], v[48:51]
	v_mfma_f32_16x16x32_bf16 v[36:39], v[188:191], v[212:215], v[36:39]
	v_mfma_f32_16x16x32_bf16 v[32:35], v[196:199], v[212:215], v[32:35]
	v_mfma_f32_16x16x32_bf16 v[20:23], v[188:191], v[220:223], v[20:23]
	v_mfma_f32_16x16x32_bf16 v[16:19], v[196:199], v[220:223], v[16:19]
	v_mfma_f32_16x16x32_bf16 v[4:7], v[188:191], v[228:231], v[4:7]
	v_mfma_f32_16x16x32_bf16 v[0:3], v[196:199], v[228:231], v[0:3]
	v_mfma_f32_16x16x32_bf16 v[52:55], v[192:195], v[208:211], v[52:55]
	v_mfma_f32_16x16x32_bf16 v[48:51], v[200:203], v[208:211], v[48:51]
	v_mfma_f32_16x16x32_bf16 v[36:39], v[192:195], v[216:219], v[36:39]
	v_mfma_f32_16x16x32_bf16 v[32:35], v[200:203], v[216:219], v[32:35]
	v_mfma_f32_16x16x32_bf16 v[20:23], v[192:195], v[224:227], v[20:23]
	v_mfma_f32_16x16x32_bf16 v[16:19], v[200:203], v[224:227], v[16:19]
	v_mfma_f32_16x16x32_bf16 v[4:7], v[192:195], v[232:235], v[4:7]
	v_mfma_f32_16x16x32_bf16 v[0:3], v[200:203], v[232:235], v[0:3]
	s_setprio 0
	s_barrier
	s_add_i32 s47, s47, 2
	s_add_u32 s25, s25, 0x100
	s_addc_u32 s46, s46, 0
	s_cmp_gt_u32 s47, s99
	s_mov_b64 s[16:17], s[18:19]
	s_cbranch_scc0 .LBB0_898
	s_and_b64 vcc, exec, s[12:13]
	s_cbranch_vccz .LBB0_901
	s_barrier
.LBB0_901:
	s_cmp_eq_u32 s99, 41
	s_cbranch_scc1 .Lsk5_epi
	v_lshrrev_b32_e32 v236, 6, v253
	v_lshlrev_b32_e32 v236, 15, v236
	v_and_b32_e32 v237, 63, v253
	v_lshl_or_b32 v236, v237, 4, v236
	s_lshr_b32 s76, s2, 1
	s_lshl_b32 s77, s76, 18
	s_add_u32 s78, s74, 0x32c58400
	s_addc_u32 s79, s75, 0
	s_add_u32 s78, s78, s77
	s_addc_u32 s79, s79, 0
	s_lshl_b32 s77, s76, 2
	s_add_u32 s82, s74, 0x1400
	s_addc_u32 s83, s75, 0
	s_add_u32 s82, s82, s77
	s_addc_u32 s83, s83, 0
	s_bitcmp1_b32 s2, 0
	s_cbranch_scc0 .Lsk5_reduce
	global_store_dwordx4 v236, v[0:3], s[78:79] sc0 sc1
	global_store_dwordx4 v236, v[4:7], s[78:79] offset:1024 sc0 sc1
	global_store_dwordx4 v236, v[8:11], s[78:79] offset:2048 sc0 sc1
	global_store_dwordx4 v236, v[12:15], s[78:79] offset:3072 sc0 sc1
	s_add_u32 s78, s78, 0x1000
	s_addc_u32 s79, s79, 0
	global_store_dwordx4 v236, v[16:19], s[78:79] sc0 sc1
	global_store_dwordx4 v236, v[20:23], s[78:79] offset:1024 sc0 sc1
	global_store_dwordx4 v236, v[24:27], s[78:79] offset:2048 sc0 sc1
	global_store_dwordx4 v236, v[28:31], s[78:79] offset:3072 sc0 sc1
	s_add_u32 s78, s78, 0x1000
	s_addc_u32 s79, s79, 0
	global_store_dwordx4 v236, v[32:35], s[78:79] sc0 sc1
	global_store_dwordx4 v236, v[36:39], s[78:79] offset:1024 sc0 sc1
	global_store_dwordx4 v236, v[40:43], s[78:79] offset:2048 sc0 sc1
	global_store_dwordx4 v236, v[44:47], s[78:79] offset:3072 sc0 sc1
	s_add_u32 s78, s78, 0x1000
	s_addc_u32 s79, s79, 0
	global_store_dwordx4 v236, v[48:51], s[78:79] sc0 sc1
	global_store_dwordx4 v236, v[52:55], s[78:79] offset:1024 sc0 sc1
	global_store_dwordx4 v236, v[56:59], s[78:79] offset:2048 sc0 sc1
	global_store_dwordx4 v236, v[60:63], s[78:79] offset:3072 sc0 sc1
	s_add_u32 s78, s78, 0x1000
	s_addc_u32 s79, s79, 0
	global_store_dwordx4 v236, v[64:67], s[78:79] sc0 sc1
	global_store_dwordx4 v236, v[68:71], s[78:79] offset:1024 sc0 sc1
	global_store_dwordx4 v236, v[72:75], s[78:79] offset:2048 sc0 sc1
	global_store_dwordx4 v236, v[76:79], s[78:79] offset:3072 sc0 sc1
	s_add_u32 s78, s78, 0x1000
	s_addc_u32 s79, s79, 0
	global_store_dwordx4 v236, v[80:83], s[78:79] sc0 sc1
	global_store_dwordx4 v236, v[84:87], s[78:79] offset:1024 sc0 sc1
	global_store_dwordx4 v236, v[88:91], s[78:79] offset:2048 sc0 sc1
	global_store_dwordx4 v236, v[92:95], s[78:79] offset:3072 sc0 sc1
	s_add_u32 s78, s78, 0x1000
	s_addc_u32 s79, s79, 0
	global_store_dwordx4 v236, v[96:99], s[78:79] sc0 sc1
	global_store_dwordx4 v236, v[100:103], s[78:79] offset:1024 sc0 sc1
	global_store_dwordx4 v236, v[104:107], s[78:79] offset:2048 sc0 sc1
	global_store_dwordx4 v236, v[108:111], s[78:79] offset:3072 sc0 sc1
	s_add_u32 s78, s78, 0x1000
	s_addc_u32 s79, s79, 0
	global_store_dwordx4 v236, v[112:115], s[78:79] sc0 sc1
	global_store_dwordx4 v236, v[116:119], s[78:79] offset:1024 sc0 sc1
	global_store_dwordx4 v236, v[120:123], s[78:79] offset:2048 sc0 sc1
	global_store_dwordx4 v236, v[124:127], s[78:79] offset:3072 sc0 sc1
	s_waitcnt vmcnt(0)
	s_barrier
	v_cmp_eq_u32_e32 vcc, 0, v253
	s_and_saveexec_b64 s[80:81], vcc
	s_cbranch_execz .Lsk5_pdone
	v_mov_b32_e32 v237, 0
	v_mov_b32_e32 v238, 1
	global_store_dword v237, v238, s[82:83] sc1
; #define PG8_BAR __builtin_amdgcn_s_barrier()
; template <class Epi, class Sched, bool ALIGN_EPI = false, bool SP2 = false>
; __device__ __forceinline__ void gemm_phase(PG8_LAS unsigned char* lds, const Gemm g, const Sched& S, const Epi& E) {
;     ...
;         }
;         if constexpr (ALIGN_EPI) { if (wr == 0) PG8_BAR; }
;         if constexpr (!Epi::AFTER_DRAIN) { E(acc, cur, wr, wc, fr, fq); S.done(cur); }
;         if (!has_next) break;
.Lsk5_pdone:
	s_or_b64 exec, exec, s[80:81]
	s_branch .LBB0_904
.Lsk5_reduce:
	v_cmp_eq_u32_e32 vcc, 0, v253
	s_and_saveexec_b64 s[80:81], vcc
	s_cbranch_execz .Lsk5_cw
	v_mov_b32_e32 v237, 0
.Lsk5_poll:
	global_load_dword v238, v237, s[82:83] sc1
	s_waitcnt vmcnt(0)
	v_cmp_ne_u32_e32 vcc, 0, v238
	s_cbranch_vccnz .Lsk5_pollok
	s_sleep 2
	s_branch .Lsk5_poll
.Lsk5_pollok:
.Lsk5_cw:
	s_or_b64 exec, exec, s[80:81]
	s_barrier
	global_load_dwordx4 v[172:175], v236, s[78:79] sc0 sc1
	global_load_dwordx4 v[176:179], v236, s[78:79] offset:1024 sc0 sc1
	global_load_dwordx4 v[180:183], v236, s[78:79] offset:2048 sc0 sc1
	global_load_dwordx4 v[184:187], v236, s[78:79] offset:3072 sc0 sc1
	s_add_u32 s78, s78, 0x1000
	s_addc_u32 s79, s79, 0
	global_load_dwordx4 v[188:191], v236, s[78:79] sc0 sc1
	global_load_dwordx4 v[192:195], v236, s[78:79] offset:1024 sc0 sc1
	global_load_dwordx4 v[196:199], v236, s[78:79] offset:2048 sc0 sc1
	global_load_dwordx4 v[200:203], v236, s[78:79] offset:3072 sc0 sc1
	s_add_u32 s78, s78, 0x1000
	s_addc_u32 s79, s79, 0
	global_load_dwordx4 v[204:207], v236, s[78:79] sc0 sc1
	global_load_dwordx4 v[208:211], v236, s[78:79] offset:1024 sc0 sc1
	global_load_dwordx4 v[212:215], v236, s[78:79] offset:2048 sc0 sc1
	global_load_dwordx4 v[216:219], v236, s[78:79] offset:3072 sc0 sc1
	s_add_u32 s78, s78, 0x1000
	s_addc_u32 s79, s79, 0
	global_load_dwordx4 v[220:223], v236, s[78:79] sc0 sc1
	global_load_dwordx4 v[224:227], v236, s[78:79] offset:1024 sc0 sc1
	global_load_dwordx4 v[228:231], v236, s[78:79] offset:2048 sc0 sc1
	global_load_dwordx4 v[232:235], v236, s[78:79] offset:3072 sc0 sc1
	s_add_u32 s78, s78, 0x1000
	s_addc_u32 s79, s79, 0
	s_waitcnt vmcnt(12)
	v_add_f32_e32 v0, v0, v172
	v_add_f32_e32 v1, v1, v173
	v_add_f32_e32 v2, v2, v174
	v_add_f32_e32 v3, v3, v175
	v_add_f32_e32 v4, v4, v176
	v_add_f32_e32 v5, v5, v177
	v_add_f32_e32 v6, v6, v178
	v_add_f32_e32 v7, v7, v179
	v_add_f32_e32 v8, v8, v180
	v_add_f32_e32 v9, v9, v181
	v_add_f32_e32 v10, v10, v182
	v_add_f32_e32 v11, v11, v183
	v_add_f32_e32 v12, v12, v184
	v_add_f32_e32 v13, v13, v185
	v_add_f32_e32 v14, v14, v186
	v_add_f32_e32 v15, v15, v187
	s_waitcnt vmcnt(8)
	v_add_f32_e32 v16, v16, v188
	v_add_f32_e32 v17, v17, v189
	v_add_f32_e32 v18, v18, v190
	v_add_f32_e32 v19, v19, v191
	v_add_f32_e32 v20, v20, v192
	v_add_f32_e32 v21, v21, v193
	v_add_f32_e32 v22, v22, v194
	v_add_f32_e32 v23, v23, v195
	v_add_f32_e32 v24, v24, v196
	v_add_f32_e32 v25, v25, v197
	v_add_f32_e32 v26, v26, v198
	v_add_f32_e32 v27, v27, v199
	v_add_f32_e32 v28, v28, v200
	v_add_f32_e32 v29, v29, v201
	v_add_f32_e32 v30, v30, v202
	v_add_f32_e32 v31, v31, v203
	s_waitcnt vmcnt(4)
	v_add_f32_e32 v32, v32, v204
	v_add_f32_e32 v33, v33, v205
	v_add_f32_e32 v34, v34, v206
	v_add_f32_e32 v35, v35, v207
	v_add_f32_e32 v36, v36, v208
	v_add_f32_e32 v37, v37, v209
	v_add_f32_e32 v38, v38, v210
	v_add_f32_e32 v39, v39, v211
	v_add_f32_e32 v40, v40, v212
	v_add_f32_e32 v41, v41, v213
	v_add_f32_e32 v42, v42, v214
	v_add_f32_e32 v43, v43, v215
	v_add_f32_e32 v44, v44, v216
	v_add_f32_e32 v45, v45, v217
	v_add_f32_e32 v46, v46, v218
	v_add_f32_e32 v47, v47, v219
	s_waitcnt vmcnt(0)
	v_add_f32_e32 v48, v48, v220
	v_add_f32_e32 v49, v49, v221
	v_add_f32_e32 v50, v50, v222
	v_add_f32_e32 v51, v51, v223
	v_add_f32_e32 v52, v52, v224
	v_add_f32_e32 v53, v53, v225
	v_add_f32_e32 v54, v54, v226
	v_add_f32_e32 v55, v55, v227
	v_add_f32_e32 v56, v56, v228
	v_add_f32_e32 v57, v57, v229
	v_add_f32_e32 v58, v58, v230
	v_add_f32_e32 v59, v59, v231
	v_add_f32_e32 v60, v60, v232
	v_add_f32_e32 v61, v61, v233
	v_add_f32_e32 v62, v62, v234
	v_add_f32_e32 v63, v63, v235
	global_load_dwordx4 v[172:175], v236, s[78:79] sc0 sc1
	global_load_dwordx4 v[176:179], v236, s[78:79] offset:1024 sc0 sc1
	global_load_dwordx4 v[180:183], v236, s[78:79] offset:2048 sc0 sc1
	global_load_dwordx4 v[184:187], v236, s[78:79] offset:3072 sc0 sc1
	s_add_u32 s78, s78, 0x1000
	s_addc_u32 s79, s79, 0
	global_load_dwordx4 v[188:191], v236, s[78:79] sc0 sc1
	global_load_dwordx4 v[192:195], v236, s[78:79] offset:1024 sc0 sc1
	global_load_dwordx4 v[196:199], v236, s[78:79] offset:2048 sc0 sc1
	global_load_dwordx4 v[200:203], v236, s[78:79] offset:3072 sc0 sc1
	s_add_u32 s78, s78, 0x1000
	s_addc_u32 s79, s79, 0
	global_load_dwordx4 v[204:207], v236, s[78:79] sc0 sc1
	global_load_dwordx4 v[208:211], v236, s[78:79] offset:1024 sc0 sc1
	global_load_dwordx4 v[212:215], v236, s[78:79] offset:2048 sc0 sc1
	global_load_dwordx4 v[216:219], v236, s[78:79] offset:3072 sc0 sc1
	s_add_u32 s78, s78, 0x1000
	s_addc_u32 s79, s79, 0
	global_load_dwordx4 v[220:223], v236, s[78:79] sc0 sc1
	global_load_dwordx4 v[224:227], v236, s[78:79] offset:1024 sc0 sc1
	global_load_dwordx4 v[228:231], v236, s[78:79] offset:2048 sc0 sc1
	global_load_dwordx4 v[232:235], v236, s[78:79] offset:3072 sc0 sc1
	s_waitcnt vmcnt(12)
	v_add_f32_e32 v64, v64, v172
	v_add_f32_e32 v65, v65, v173
	v_add_f32_e32 v66, v66, v174
	v_add_f32_e32 v67, v67, v175
	v_add_f32_e32 v68, v68, v176
	v_add_f32_e32 v69, v69, v177
	v_add_f32_e32 v70, v70, v178
	v_add_f32_e32 v71, v71, v179
	v_add_f32_e32 v72, v72, v180
	v_add_f32_e32 v73, v73, v181
	v_add_f32_e32 v74, v74, v182
	v_add_f32_e32 v75, v75, v183
	v_add_f32_e32 v76, v76, v184
	v_add_f32_e32 v77, v77, v185
	v_add_f32_e32 v78, v78, v186
	v_add_f32_e32 v79, v79, v187
	s_waitcnt vmcnt(8)
	v_add_f32_e32 v80, v80, v188
	v_add_f32_e32 v81, v81, v189
	v_add_f32_e32 v82, v82, v190
	v_add_f32_e32 v83, v83, v191
	v_add_f32_e32 v84, v84, v192
	v_add_f32_e32 v85, v85, v193
	v_add_f32_e32 v86, v86, v194
	v_add_f32_e32 v87, v87, v195
	v_add_f32_e32 v88, v88, v196
	v_add_f32_e32 v89, v89, v197
	v_add_f32_e32 v90, v90, v198
	v_add_f32_e32 v91, v91, v199
	v_add_f32_e32 v92, v92, v200
	v_add_f32_e32 v93, v93, v201
	v_add_f32_e32 v94, v94, v202
	v_add_f32_e32 v95, v95, v203
	s_waitcnt vmcnt(4)
	v_add_f32_e32 v96, v96, v204
	v_add_f32_e32 v97, v97, v205
	v_add_f32_e32 v98, v98, v206
	v_add_f32_e32 v99, v99, v207
	v_add_f32_e32 v100, v100, v208
	v_add_f32_e32 v101, v101, v209
	v_add_f32_e32 v102, v102, v210
	v_add_f32_e32 v103, v103, v211
	v_add_f32_e32 v104, v104, v212
	v_add_f32_e32 v105, v105, v213
	v_add_f32_e32 v106, v106, v214
	v_add_f32_e32 v107, v107, v215
	v_add_f32_e32 v108, v108, v216
	v_add_f32_e32 v109, v109, v217
	v_add_f32_e32 v110, v110, v218
	v_add_f32_e32 v111, v111, v219
	s_waitcnt vmcnt(0)
	v_add_f32_e32 v112, v112, v220
	v_add_f32_e32 v113, v113, v221
	v_add_f32_e32 v114, v114, v222
	v_add_f32_e32 v115, v115, v223
	v_add_f32_e32 v116, v116, v224
	v_add_f32_e32 v117, v117, v225
	v_add_f32_e32 v118, v118, v226
	v_add_f32_e32 v119, v119, v227
	v_add_f32_e32 v120, v120, v228
	v_add_f32_e32 v121, v121, v229
	v_add_f32_e32 v122, v122, v230
	v_add_f32_e32 v123, v123, v231
	v_add_f32_e32 v124, v124, v232
	v_add_f32_e32 v125, v125, v233
	v_add_f32_e32 v126, v126, v234
	v_add_f32_e32 v127, v127, v235
